# GEMM k-loops: per-cluster s_setprio flips removed, one static raise for younger workgroups (bid>=256); epilogue LN2 gamma/beta loads hoisted
# speedup vs baseline: 1.0395x; 1.0091x over previous
; template <int MODE>
; DI void gemm_phase(const Params& p, int layer, char* smem, const u16* A, const u16* Bt, int Mtiles, int Ntiles, const bool dry) {
;     ...
;   for (int ch = xcd; ch < nchunks; ch += 8)
;   for (int jj = jx; jj < 64; jj += wpx) {
;     const int L = ch * 64 + jj;
;     if (L >= ntiles) continue;
;     const int mt = (L / (4 * Ntiles)) * 4 + (L & 3), nt = (L >> 2) % Ntiles;
;     const u16* Ag = A + ((size_t)mt * 256 + srow) * D + sc8;
;     const u16* Bg = Bt + ((size_t)nt * 128 + srow) * D + sc8;
;     f32x16 acc[4][2];
; #pragma unroll
;     for (int i = 0; i < 4; i++)
; #pragma unroll
;       for (int j = 0; j < 2; j++)
; #pragma unroll
;         for (int e = 0; e < 16; e++) acc[i][j][e] = 0.f;
;     bf16x8 ra0, ra1, ra2, ra3, ra4, ra5, ra6, ra7, rb0, rb1, rb2, rb3;
;     ...
;     GLOAD(0)
;     __syncthreads();
;     LSTORE()
;     __syncthreads();
.LBB0_237:
	s_add_i32 s4, s50, s48
	s_cmpk_gt_i32 s4, 0x1103
	s_cbranch_scc1 .LBB0_236
	s_mul_hi_i32 s5, s4, 0x3e0f83e1
	s_lshr_b32 s20, s5, 31
	s_ashr_i32 s5, s5, 5
	s_add_i32 s5, s5, s20
	s_lshl_b32 s20, s5, 2
	s_and_b32 s5, s50, 3
	s_ashr_i32 s4, s4, 2
	s_or_b32 s36, s20, s5
	s_mul_hi_i32 s5, s4, 0x3e0f83e1
	s_lshr_b32 s21, s5, 31
	s_ashr_i32 s5, s5, 3
	s_add_i32 s5, s5, s21
	s_mul_i32 s5, s5, 33
	s_ashr_i32 s37, s36, 31
	s_sub_i32 s38, s4, s5
	s_cmp_ge_u32 s74, 0x100
	s_cbranch_scc0 .Lprio_skip_3
	s_setprio 1
.Lprio_skip_3:
	s_lshl_b64 s[4:5], s[36:37], 19
	s_waitcnt lgkmcnt(0)
	v_lshl_add_u64 v[0:1], v[176:177], 0, s[4:5]
	v_add_co_u32_e32 v4, vcc, s91, v0
	global_load_dwordx4 v[128:131], v[0:1], off
	s_nop 0
	v_addc_co_u32_e32 v5, vcc, 0, v1, vcc
	v_add_co_u32_e32 v6, vcc, s89, v0
	s_ashr_i32 s39, s38, 31
	s_nop 0
	v_addc_co_u32_e32 v7, vcc, 0, v1, vcc
	global_load_dwordx4 v[132:135], v[4:5], off
	global_load_dwordx4 v[136:139], v[6:7], off
	v_add_co_u32_e32 v4, vcc, s23, v0
	s_mov_b32 s4, 0x70000
	s_nop 0
	v_addc_co_u32_e32 v5, vcc, 0, v1, vcc
	v_add_co_u32_e32 v6, vcc, s26, v0
	s_lshl_b64 s[40:41], s[38:39], 18
	s_nop 0
	v_addc_co_u32_e32 v7, vcc, 0, v1, vcc
	global_load_dwordx4 v[140:143], v[4:5], off
	global_load_dwordx4 v[144:147], v[6:7], off
	v_add_co_u32_e32 v4, vcc, s27, v0
	v_lshl_add_u64 v[2:3], v[178:179], 0, s[40:41]
	s_nop 0
	v_addc_co_u32_e32 v5, vcc, 0, v1, vcc
	v_add_co_u32_e32 v6, vcc, s51, v0
	v_lshl_add_u64 v[194:195], v[190:191], 0, s[40:41]
	s_nop 0
	v_addc_co_u32_e32 v7, vcc, 0, v1, vcc
	v_add_co_u32_e32 v0, vcc, s4, v0
	global_load_dwordx4 v[148:151], v[4:5], off
	global_load_dwordx4 v[152:155], v[6:7], off
	v_addc_co_u32_e32 v1, vcc, 0, v1, vcc
	global_load_dwordx4 v[156:159], v[0:1], off
	global_load_dwordx4 v[160:163], v[2:3], off
	v_add_co_u32_e32 v0, vcc, s91, v2
	s_and_b32 s4, s49, 3
	s_nop 0
	v_addc_co_u32_e32 v1, vcc, 0, v3, vcc
	v_add_co_u32_e32 v4, vcc, s89, v2
	s_or_b32 s4, s20, s4
	s_nop 0
	v_addc_co_u32_e32 v5, vcc, 0, v3, vcc
	global_load_dwordx4 v[164:167], v[0:1], off
	global_load_dwordx4 v[168:171], v[4:5], off
	v_add_co_u32_e32 v0, vcc, s23, v2
	s_ashr_i32 s5, s4, 31
	s_nop 0
	v_addc_co_u32_e32 v1, vcc, 0, v3, vcc
	global_load_dwordx4 v[172:175], v[0:1], off
	s_lshl_b64 s[4:5], s[4:5], 19
	v_mov_b32_e32 v0, 0
	v_lshl_add_u64 v[192:193], v[188:189], 0, s[4:5]
	s_mov_b64 s[40:41], 0
	v_mov_b32_e32 v1, v0
	v_mov_b32_e32 v2, v0
	v_mov_b32_e32 v3, v0
	v_mov_b32_e32 v4, v0
	v_mov_b32_e32 v5, v0
	v_mov_b32_e32 v6, v0
	v_mov_b32_e32 v7, v0
	v_mov_b32_e32 v8, v0
	v_mov_b32_e32 v9, v0
	v_mov_b32_e32 v10, v0
	v_mov_b32_e32 v11, v0
	s_waitcnt vmcnt(12)
	v_mov_b32_e32 v12, v0
	v_mov_b32_e32 v13, v0
	v_mov_b32_e32 v14, v0
	v_mov_b32_e32 v15, v0
	v_mov_b32_e32 v16, v0
	v_mov_b32_e32 v17, v0
	v_mov_b32_e32 v18, v0
	v_mov_b32_e32 v19, v0
	v_mov_b32_e32 v20, v0
	v_mov_b32_e32 v21, v0
	v_mov_b32_e32 v22, v0
	v_mov_b32_e32 v23, v0
	v_mov_b32_e32 v24, v0
	v_mov_b32_e32 v25, v0
	v_mov_b32_e32 v26, v0
	v_mov_b32_e32 v27, v0
	v_mov_b32_e32 v28, v0
	v_mov_b32_e32 v29, v0
	v_mov_b32_e32 v30, v0
	v_mov_b32_e32 v31, v0
	v_mov_b32_e32 v32, v0
	v_mov_b32_e32 v33, v0
	v_mov_b32_e32 v34, v0
	v_mov_b32_e32 v35, v0
	v_mov_b32_e32 v36, v0
	v_mov_b32_e32 v37, v0
	v_mov_b32_e32 v38, v0
	v_mov_b32_e32 v39, v0
	v_mov_b32_e32 v40, v0
	v_mov_b32_e32 v41, v0
	v_mov_b32_e32 v42, v0
	v_mov_b32_e32 v43, v0
	v_mov_b32_e32 v44, v0
	v_mov_b32_e32 v45, v0
	v_mov_b32_e32 v46, v0
	v_mov_b32_e32 v47, v0
	v_mov_b32_e32 v48, v0
	v_mov_b32_e32 v49, v0
	v_mov_b32_e32 v50, v0
	v_mov_b32_e32 v51, v0
	v_mov_b32_e32 v52, v0
	v_mov_b32_e32 v53, v0
	v_mov_b32_e32 v54, v0
	v_mov_b32_e32 v55, v0
	v_mov_b32_e32 v56, v0
	v_mov_b32_e32 v57, v0
	v_mov_b32_e32 v58, v0
	v_mov_b32_e32 v59, v0
	v_mov_b32_e32 v60, v0
	v_mov_b32_e32 v61, v0
	v_mov_b32_e32 v62, v0
	v_mov_b32_e32 v63, v0
	v_mov_b32_e32 v64, v0
	v_mov_b32_e32 v65, v0
	v_mov_b32_e32 v66, v0
	v_mov_b32_e32 v67, v0
	v_mov_b32_e32 v68, v0
	v_mov_b32_e32 v69, v0
	v_mov_b32_e32 v70, v0
	v_mov_b32_e32 v71, v0
	v_mov_b32_e32 v72, v0
	v_mov_b32_e32 v73, v0
	v_mov_b32_e32 v74, v0
	v_mov_b32_e32 v75, v0
	v_mov_b32_e32 v76, v0
	v_mov_b32_e32 v77, v0
	v_mov_b32_e32 v78, v0
	v_mov_b32_e32 v79, v0
	v_mov_b32_e32 v80, v0
	v_mov_b32_e32 v81, v0
	v_mov_b32_e32 v82, v0
	v_mov_b32_e32 v83, v0
	v_mov_b32_e32 v84, v0
	v_mov_b32_e32 v85, v0
	v_mov_b32_e32 v86, v0
	v_mov_b32_e32 v87, v0
	v_mov_b32_e32 v88, v0
	v_mov_b32_e32 v89, v0
	v_mov_b32_e32 v90, v0
	v_mov_b32_e32 v91, v0
	v_mov_b32_e32 v92, v0
	v_mov_b32_e32 v93, v0
	v_mov_b32_e32 v94, v0
	v_mov_b32_e32 v95, v0
	v_mov_b32_e32 v96, v0
	v_mov_b32_e32 v97, v0
	v_mov_b32_e32 v98, v0
	v_mov_b32_e32 v99, v0
	v_mov_b32_e32 v100, v0
	v_mov_b32_e32 v101, v0
	v_mov_b32_e32 v102, v0
	v_mov_b32_e32 v103, v0
	v_mov_b32_e32 v104, v0
	v_mov_b32_e32 v105, v0
	v_mov_b32_e32 v106, v0
	v_mov_b32_e32 v107, v0
	v_mov_b32_e32 v108, v0
	v_mov_b32_e32 v109, v0
	v_mov_b32_e32 v110, v0
	v_mov_b32_e32 v111, v0
	v_mov_b32_e32 v112, v0
	v_mov_b32_e32 v113, v0
	v_mov_b32_e32 v114, v0
	v_mov_b32_e32 v115, v0
	v_mov_b32_e32 v116, v0
	v_mov_b32_e32 v117, v0
	v_mov_b32_e32 v118, v0
	v_mov_b32_e32 v119, v0
	v_mov_b32_e32 v120, v0
	v_mov_b32_e32 v121, v0
	v_mov_b32_e32 v122, v0
	v_mov_b32_e32 v123, v0
	v_mov_b32_e32 v124, v0
	v_mov_b32_e32 v125, v0
	v_mov_b32_e32 v126, v0
	v_mov_b32_e32 v127, v0
	s_barrier
	s_waitcnt vmcnt(11)
	ds_write_b128 v180, v[128:131]
	s_waitcnt vmcnt(10)
	ds_write_b128 v180, v[132:135] offset:4608
	s_waitcnt vmcnt(9)
	ds_write_b128 v180, v[136:139] offset:9216
	s_waitcnt vmcnt(8)
	ds_write_b128 v180, v[140:143] offset:13824
	s_waitcnt vmcnt(7)
	ds_write_b128 v180, v[144:147] offset:18432
	s_waitcnt vmcnt(6)
	ds_write_b128 v180, v[148:151] offset:23040
	s_waitcnt vmcnt(5)
	ds_write_b128 v180, v[152:155] offset:27648
	s_waitcnt vmcnt(4)
	ds_write_b128 v180, v[156:159] offset:32256
	s_waitcnt vmcnt(3)
	ds_write_b128 v180, v[160:163] offset:36864
	s_waitcnt vmcnt(2)
	ds_write_b128 v180, v[164:167] offset:41472
	s_waitcnt vmcnt(1)
	ds_write_b128 v180, v[168:171] offset:46080
	s_waitcnt vmcnt(0)
	ds_write_b128 v180, v[172:175] offset:50688
	s_waitcnt lgkmcnt(0)
	s_barrier
	s_branch .LBB0_240

; #define MFMA32(a, b, c) __builtin_amdgcn_mfma_f32_32x32x16_bf16((a), (b), (c), 0, 0, 0)
; template <int MODE>
; DI void gemm_phase(const Params& p, int layer, char* smem, const u16* A, const u16* Bt, int Mtiles, int Ntiles, const bool dry) {
;     ...
;     for (int kt = 0; kt < 16; kt++) {
;       if (kt + 1 < 16 && !(dry && DRYVAR == 1)) GLOAD(kt + 1)
;       const u16* as = As + (wm * 128 + r) * LDS_STRIDE + h * 8;
;       const u16* bs = Bs + (wn * 64 + r) * LDS_STRIDE + h * 8;
;       if (!(dry && DRYVAR == 2)) {
;         bf16x8 af[2][4], b0, b1;
; #pragma unroll
;         for (int i = 0; i < 4; i++) af[0][i] = *(const bf16x8*)(as + i * 32 * LDS_STRIDE);
;         b0 = *(const bf16x8*)(bs); b1 = *(const bf16x8*)(bs + 32 * LDS_STRIDE);
; #pragma unroll
;         for (int kk = 0; kk < 4; kk++) {
;           const int cur = kk & 1, nxt = cur ^ 1;
;           if (kk < 3) {
; #pragma unroll
;             for (int i = 0; i < 4; i++) af[nxt][i] = *(const bf16x8*)(as + i * 32 * LDS_STRIDE + (kk + 1) * 16);
;           }
;           __builtin_amdgcn_s_setprio(1);
; #pragma unroll
;           for (int i = 0; i < 4; i++) acc[i][0] = MFMA32(af[cur][i], b0, acc[i][0]);
;           if (kk < 3) b0 = *(const bf16x8*)(bs + (kk + 1) * 16);
; #pragma unroll
;           for (int i = 0; i < 4; i++) acc[i][1] = MFMA32(af[cur][i], b1, acc[i][1]);
;           if (kk < 3) b1 = *(const bf16x8*)(bs + 32 * LDS_STRIDE + (kk + 1) * 16);
;           __builtin_amdgcn_s_setprio(0);
;         }
;       }
;       __syncthreads();
;       if (kt + 1 < 16 && !(dry && DRYVAR == 1)) LSTORE()
;       __syncthreads();
.LBB0_242:
	ds_read_b128 v[198:201], v181 offset:36864
	ds_read_b128 v[202:205], v181 offset:41472
	ds_read_b128 v[206:209], v182
	ds_read_b128 v[210:213], v182 offset:32
	ds_read_b128 v[214:217], v182 offset:4608
	ds_read_b128 v[230:233], v182 offset:4640
	ds_read_b128 v[234:237], v182 offset:9216
	ds_read_b128 v[238:241], v182 offset:9248
	ds_read_b128 v[242:245], v182 offset:13824
	ds_read_b128 v[246:249], v182 offset:13856
	s_waitcnt lgkmcnt(7)
	v_mfma_f32_32x32x16_bf16 v[112:127], v[206:209], v[198:201], v[112:127]
	s_waitcnt lgkmcnt(5)
	v_mfma_f32_32x32x16_bf16 v[80:95], v[214:217], v[198:201], v[80:95]
	s_waitcnt lgkmcnt(3)
	v_mfma_f32_32x32x16_bf16 v[48:63], v[234:237], v[198:201], v[48:63]
	s_waitcnt lgkmcnt(1)
	v_mfma_f32_32x32x16_bf16 v[16:31], v[242:245], v[198:201], v[16:31]
	v_mfma_f32_32x32x16_bf16 v[96:111], v[206:209], v[202:205], v[96:111]
	ds_read_b128 v[198:201], v181 offset:36896
	ds_read_b128 v[206:209], v181 offset:41504
	v_mfma_f32_32x32x16_bf16 v[64:79], v[214:217], v[202:205], v[64:79]
	v_mfma_f32_32x32x16_bf16 v[32:47], v[234:237], v[202:205], v[32:47]
	v_mfma_f32_32x32x16_bf16 v[0:15], v[242:245], v[202:205], v[0:15]
	ds_read_b128 v[202:205], v182 offset:64
	ds_read_b128 v[214:217], v182 offset:4672
	ds_read_b128 v[234:237], v182 offset:9280
	ds_read_b128 v[242:245], v182 offset:13888
	s_waitcnt lgkmcnt(5)
	v_mfma_f32_32x32x16_bf16 v[112:127], v[210:213], v[198:201], v[112:127]
	v_mfma_f32_32x32x16_bf16 v[80:95], v[230:233], v[198:201], v[80:95]
	v_mfma_f32_32x32x16_bf16 v[48:63], v[238:241], v[198:201], v[48:63]
	v_mfma_f32_32x32x16_bf16 v[16:31], v[246:249], v[198:201], v[16:31]
	s_waitcnt lgkmcnt(4)
	v_mfma_f32_32x32x16_bf16 v[96:111], v[210:213], v[206:209], v[96:111]
	ds_read_b128 v[198:201], v181 offset:36928
	ds_read_b128 v[210:213], v181 offset:41536
	v_mfma_f32_32x32x16_bf16 v[64:79], v[230:233], v[206:209], v[64:79]
	v_mfma_f32_32x32x16_bf16 v[32:47], v[238:241], v[206:209], v[32:47]
	v_mfma_f32_32x32x16_bf16 v[0:15], v[246:249], v[206:209], v[0:15]
	ds_read_b128 v[206:209], v182 offset:96
	ds_read_b128 v[230:233], v182 offset:4704
	ds_read_b128 v[238:241], v182 offset:9312
	ds_read_b128 v[246:249], v182 offset:13920
	s_waitcnt lgkmcnt(5)
	v_mfma_f32_32x32x16_bf16 v[112:127], v[202:205], v[198:201], v[112:127]
	v_mfma_f32_32x32x16_bf16 v[80:95], v[214:217], v[198:201], v[80:95]
	v_mfma_f32_32x32x16_bf16 v[48:63], v[234:237], v[198:201], v[48:63]
	v_mfma_f32_32x32x16_bf16 v[16:31], v[242:245], v[198:201], v[16:31]
	s_waitcnt lgkmcnt(4)
	v_mfma_f32_32x32x16_bf16 v[96:111], v[202:205], v[210:213], v[96:111]
	ds_read_b128 v[198:201], v181 offset:36960
	ds_read_b128 v[202:205], v181 offset:41568
	v_mfma_f32_32x32x16_bf16 v[64:79], v[214:217], v[210:213], v[64:79]
	v_mfma_f32_32x32x16_bf16 v[32:47], v[234:237], v[210:213], v[32:47]
	v_mfma_f32_32x32x16_bf16 v[0:15], v[242:245], v[210:213], v[0:15]
	s_waitcnt lgkmcnt(1)
	v_mfma_f32_32x32x16_bf16 v[112:127], v[206:209], v[198:201], v[112:127]
	v_mfma_f32_32x32x16_bf16 v[80:95], v[230:233], v[198:201], v[80:95]
	v_mfma_f32_32x32x16_bf16 v[48:63], v[238:241], v[198:201], v[48:63]
	v_mfma_f32_32x32x16_bf16 v[16:31], v[246:249], v[198:201], v[16:31]
	s_waitcnt lgkmcnt(0)
	v_mfma_f32_32x32x16_bf16 v[96:111], v[206:209], v[202:205], v[96:111]
	v_mfma_f32_32x32x16_bf16 v[64:79], v[230:233], v[202:205], v[64:79]
	v_mfma_f32_32x32x16_bf16 v[32:47], v[238:241], v[202:205], v[32:47]
	v_mfma_f32_32x32x16_bf16 v[0:15], v[246:249], v[202:205], v[0:15]
	s_andn2_b64 vcc, exec, s[42:43]
	s_barrier
	s_cbranch_vccnz .LBB0_239
	s_waitcnt vmcnt(11)
	ds_write_b128 v180, v[128:131]
	s_waitcnt vmcnt(10)
	ds_write_b128 v180, v[132:135] offset:4608
	s_waitcnt vmcnt(9)
	ds_write_b128 v180, v[136:139] offset:9216
	s_waitcnt vmcnt(8)
	ds_write_b128 v180, v[140:143] offset:13824
	s_waitcnt vmcnt(7)
	ds_write_b128 v180, v[144:147] offset:18432
	s_waitcnt vmcnt(6)
	ds_write_b128 v180, v[148:151] offset:23040
	s_waitcnt vmcnt(5)
	ds_write_b128 v180, v[152:155] offset:27648
	s_waitcnt vmcnt(4)
	ds_write_b128 v180, v[156:159] offset:32256
	s_waitcnt vmcnt(3)
	ds_write_b128 v180, v[160:163] offset:36864
	s_waitcnt vmcnt(2)
	ds_write_b128 v180, v[164:167] offset:41472
	s_waitcnt vmcnt(1)
	ds_write_b128 v180, v[168:171] offset:46080
	s_waitcnt vmcnt(0)
	ds_write_b128 v180, v[172:175] offset:50688
	s_branch .LBB0_239
; DI int crow(int i, int h) { return (i & 3) + 8 * (i >> 2) + 4 * h; }
; template <int MODE>
; DI void gemm_phase(const Params& p, int layer, char* smem, const u16* A, const u16* Bt, int Mtiles, int Ntiles, const bool dry) {
;     ...
;     const int m0 = mt * 256, n0 = nt * 128;
;     const int c4 = (tid & 31) * 4, rr0 = tid >> 5;
; #pragma unroll
;     for (int ph = 0; ph < 2; ph++) {
;       if (ph) __syncthreads();
; #pragma unroll
;       for (int ii = 0; ii < 2; ii++)
; #pragma unroll
;         for (int j = 0; j < 2; j++)
; #pragma unroll
;           for (int e = 0; e < 16; e++) Ct[(wm * 64 + ii * 32 + crow(e, h)) * CT_STRIDE + wn * 64 + j * 32 + r] = acc[ph * 2 + ii][j][e];
;       __syncthreads();
.LBB0_244:
	s_setprio 0
	ds_write2_b32 v186, v112, v96 offset1:32
	ds_write2_b32 v186, v113, v97 offset0:132 offset1:164
	v_add_u32_e32 v96, 0x400, v186
	ds_write2_b32 v96, v114, v98 offset0:8 offset1:40
	ds_write2_b32 v96, v115, v99 offset0:140 offset1:172
	v_add_u32_e32 v97, 0x1000, v186
	v_add_u32_e32 v98, 0x1400, v186
	v_add_u32_e32 v99, 0x2000, v186
	ds_write2_b32 v97, v116, v100 offset0:32 offset1:64
	ds_write2_b32 v97, v117, v101 offset0:164 offset1:196
	ds_write2_b32 v98, v118, v102 offset0:40 offset1:72
	ds_write2_b32 v98, v119, v103 offset0:172 offset1:204
	ds_write2_b32 v99, v120, v104 offset0:64 offset1:96
	ds_write2_b32 v99, v121, v105 offset0:196 offset1:228
	v_add_u32_e32 v100, 0x2400, v186
	v_add_u32_e32 v105, 0x4000, v186
	ds_write2_b32 v100, v122, v106 offset0:72 offset1:104
	ds_write2_b32 v100, v123, v107 offset0:204 offset1:236
	v_add_u32_e32 v101, 0x3000, v186
	v_add_u32_e32 v102, 0x3200, v186
	v_add_u32_e32 v103, 0x3400, v186
	v_add_u32_e32 v104, 0x3600, v186
	ds_write2_b32 v105, v80, v64 offset0:128 offset1:160
	v_add_u32_e32 v80, 0x4400, v186
	ds_write2_b32 v101, v124, v108 offset0:96 offset1:128
	ds_write2_b32 v102, v125, v109 offset0:100 offset1:132
	ds_write2_b32 v103, v126, v110 offset0:104 offset1:136
	ds_write2_b32 v104, v127, v111 offset0:108 offset1:140
	ds_write2_b32 v80, v81, v65 offset0:4 offset1:36
	ds_write2_b32 v80, v82, v66 offset0:136 offset1:168
	v_add_u32_e32 v81, 0x4800, v186
	s_lshl_b32 s4, s38, 7
	ds_write2_b32 v81, v83, v67 offset0:12 offset1:44
	v_add_u32_e32 v82, 0x5000, v186
	v_add_u32_e32 v83, 0x5400, v186
	s_ashr_i32 s5, s4, 31
	ds_write2_b32 v82, v84, v68 offset0:160 offset1:192
	ds_write2_b32 v83, v85, v69 offset0:36 offset1:68
	ds_write2_b32 v83, v86, v70 offset0:168 offset1:200
	v_add_u32_e32 v85, 0x6000, v186
	s_lshl_b32 s30, s36, 8
	s_and_b32 s20, s38, -4
	s_waitcnt vmcnt(11)
	v_or_b32_e32 v128, s4, v184
	v_add_u32_e32 v84, 0x5800, v186
	ds_write2_b32 v85, v88, v72 offset0:192 offset1:224
	v_add_u32_e32 v72, 0x6400, v186
	s_lshl_b64 s[4:5], s[4:5], 1
	ds_write2_b32 v84, v87, v71 offset0:44 offset1:76
	ds_write2_b32 v72, v89, v73 offset0:68 offset1:100
	ds_write2_b32 v72, v90, v74 offset0:200 offset1:232
	v_add_u32_e32 v73, 0x6800, v186
	s_add_u32 s38, s12, s4
	ds_write2_b32 v73, v91, v75 offset0:76 offset1:108
	v_add_u32_e32 v74, 0x7200, v186
	v_add_u32_e32 v75, 0x7400, v186
	s_addc_u32 s39, s13, s5
	s_movk_i32 s21, 0x1020
	ds_write2_b32 v74, v92, v76 offset0:96 offset1:128
	ds_write2_b32 v75, v93, v77 offset0:100 offset1:132
	v_add_u32_e32 v76, 0x7600, v186
	v_add_u32_e32 v77, 0x7800, v186
	s_add_u32 s40, s14, s4
	v_cmp_gt_i32_e64 s[36:37], s21, v128
	ds_write2_b32 v76, v94, v78 offset0:104 offset1:136
	ds_write2_b32 v77, v95, v79 offset0:108 offset1:140
	s_addc_u32 s41, s15, s5
	s_mov_b32 s31, 0
	v_mov_b32_e32 v78, v187
	v_mov_b32_e32 v79, v183
	s_waitcnt lgkmcnt(0)
	s_barrier
	s_branch .LBB0_246

; template <int MODE>
; DI void gemm_phase(const Params& p, int layer, char* smem, const u16* A, const u16* Bt, int Mtiles, int Ntiles, const bool dry) {
;     ...
;   for (int ch = xcd; ch < nchunks; ch += 8)
;   for (int jj = jx; jj < 64; jj += wpx) {
;     const int L = ch * 64 + jj;
;     if (L >= ntiles) continue;
;     const int mt = (L / (4 * Ntiles)) * 4 + (L & 3), nt = (L >> 2) % Ntiles;
;     const u16* Ag = A + ((size_t)mt * 256 + srow) * D + sc8;
;     const u16* Bg = Bt + ((size_t)nt * 128 + srow) * D + sc8;
;     f32x16 acc[4][2];
; #pragma unroll
;     for (int i = 0; i < 4; i++)
; #pragma unroll
;       for (int j = 0; j < 2; j++)
; #pragma unroll
;         for (int e = 0; e < 16; e++) acc[i][j][e] = 0.f;
;     bf16x8 ra0, ra1, ra2, ra3, ra4, ra5, ra6, ra7, rb0, rb1, rb2, rb3;
;     ...
;     GLOAD(0)
;     __syncthreads();
;     LSTORE()
;     __syncthreads();
.LBB0_741:
	s_add_i32 s4, s53, s51
	s_ashr_i32 s5, s4, 31
	s_lshr_b32 s5, s5, 27
	s_add_i32 s5, s4, s5
	s_ashr_i32 s5, s5, 5
	s_lshl_b32 s20, s5, 2
	s_and_b32 s5, s53, 3
	s_ashr_i32 s4, s4, 2
	s_or_b32 s38, s20, s5
	s_lshr_b32 s5, s4, 29
	s_add_i32 s5, s4, s5
	s_and_b32 s5, s5, -8
	s_ashr_i32 s39, s38, 31
	s_sub_i32 s44, s4, s5
	s_cmp_ge_u32 s74, 0x100
	s_cbranch_scc0 .Lprio_skip_2
	s_setprio 1
.Lprio_skip_2:
	s_lshl_b64 s[4:5], s[38:39], 19
	v_lshl_add_u64 v[0:1], v[176:177], 0, s[4:5]
	v_add_co_u32_e32 v4, vcc, s91, v0
	global_load_dwordx4 v[128:131], v[0:1], off
	s_nop 0
	v_addc_co_u32_e32 v5, vcc, 0, v1, vcc
	v_add_co_u32_e32 v6, vcc, s89, v0
	s_mov_b32 s4, 0x40000
	s_nop 0
	v_addc_co_u32_e32 v7, vcc, 0, v1, vcc
	global_load_dwordx4 v[132:135], v[4:5], off
	global_load_dwordx4 v[136:139], v[6:7], off
	v_add_co_u32_e32 v4, vcc, s23, v0
	s_ashr_i32 s45, s44, 31
	s_nop 0
	v_addc_co_u32_e32 v5, vcc, 0, v1, vcc
	v_add_co_u32_e32 v6, vcc, s4, v0
	s_mov_b32 s4, 0x50000
	s_nop 0
	v_addc_co_u32_e32 v7, vcc, 0, v1, vcc
	global_load_dwordx4 v[140:143], v[4:5], off
	global_load_dwordx4 v[144:147], v[6:7], off
	v_add_co_u32_e32 v4, vcc, s4, v0
	s_mov_b32 s4, 0x60000
	s_nop 0
	v_addc_co_u32_e32 v5, vcc, 0, v1, vcc
	s_lshl_b64 s[46:47], s[44:45], 18
	v_add_co_u32_e32 v6, vcc, s4, v0
	v_lshl_add_u64 v[2:3], v[178:179], 0, s[46:47]
	s_nop 0
	v_addc_co_u32_e32 v7, vcc, 0, v1, vcc
	v_add_co_u32_e32 v8, vcc, s91, v2
	global_load_dwordx4 v[148:151], v[2:3], off
	s_nop 0
	v_addc_co_u32_e32 v9, vcc, 0, v3, vcc
	v_add_co_u32_e32 v10, vcc, s89, v2
	s_mov_b32 s4, 0x70000
	s_nop 0
	v_addc_co_u32_e32 v11, vcc, 0, v3, vcc
	v_add_co_u32_e32 v2, vcc, s23, v2
	global_load_dwordx4 v[160:163], v[8:9], off
	global_load_dwordx4 v[168:171], v[10:11], off
	v_addc_co_u32_e32 v3, vcc, 0, v3, vcc
	v_add_co_u32_e32 v0, vcc, s4, v0
	global_load_dwordx4 v[172:175], v[2:3], off
	global_load_dwordx4 v[152:155], v[4:5], off
	global_load_dwordx4 v[156:159], v[6:7], off
	v_addc_co_u32_e32 v1, vcc, 0, v1, vcc
	global_load_dwordx4 v[164:167], v[0:1], off
	s_and_b32 s4, s52, 3
	s_or_b32 s4, s20, s4
	s_ashr_i32 s5, s4, 31
	s_lshl_b64 s[4:5], s[4:5], 19
	v_mov_b32_e32 v0, 0
	v_lshl_add_u64 v[194:195], v[190:191], 0, s[4:5]
	v_lshl_add_u64 v[198:199], v[192:193], 0, s[46:47]
	s_mov_b64 s[46:47], 0
	v_mov_b32_e32 v1, v0
	v_mov_b32_e32 v2, v0
	v_mov_b32_e32 v3, v0
	v_mov_b32_e32 v4, v0
	v_mov_b32_e32 v5, v0
	v_mov_b32_e32 v6, v0
	v_mov_b32_e32 v7, v0
	v_mov_b32_e32 v8, v0
	v_mov_b32_e32 v9, v0
	v_mov_b32_e32 v10, v0
	v_mov_b32_e32 v11, v0
	s_waitcnt vmcnt(12)
	v_mov_b32_e32 v12, v0
	v_mov_b32_e32 v13, v0
	v_mov_b32_e32 v14, v0
	v_mov_b32_e32 v15, v0
	v_mov_b32_e32 v16, v0
	v_mov_b32_e32 v17, v0
	v_mov_b32_e32 v18, v0
	v_mov_b32_e32 v19, v0
	v_mov_b32_e32 v20, v0
	v_mov_b32_e32 v21, v0
	v_mov_b32_e32 v22, v0
	v_mov_b32_e32 v23, v0
	v_mov_b32_e32 v24, v0
	v_mov_b32_e32 v25, v0
	v_mov_b32_e32 v26, v0
	v_mov_b32_e32 v27, v0
	v_mov_b32_e32 v28, v0
	v_mov_b32_e32 v29, v0
	v_mov_b32_e32 v30, v0
	v_mov_b32_e32 v31, v0
	v_mov_b32_e32 v32, v0
	v_mov_b32_e32 v33, v0
	v_mov_b32_e32 v34, v0
	v_mov_b32_e32 v35, v0
	v_mov_b32_e32 v36, v0
	v_mov_b32_e32 v37, v0
	v_mov_b32_e32 v38, v0
	v_mov_b32_e32 v39, v0
	v_mov_b32_e32 v40, v0
	v_mov_b32_e32 v41, v0
	v_mov_b32_e32 v42, v0
	v_mov_b32_e32 v43, v0
	v_mov_b32_e32 v44, v0
	v_mov_b32_e32 v45, v0
	v_mov_b32_e32 v46, v0
	v_mov_b32_e32 v47, v0
	v_mov_b32_e32 v48, v0
	v_mov_b32_e32 v49, v0
	v_mov_b32_e32 v50, v0
	v_mov_b32_e32 v51, v0
	v_mov_b32_e32 v52, v0
	v_mov_b32_e32 v53, v0
	v_mov_b32_e32 v54, v0
	v_mov_b32_e32 v55, v0
	v_mov_b32_e32 v56, v0
	v_mov_b32_e32 v57, v0
	v_mov_b32_e32 v58, v0
	v_mov_b32_e32 v59, v0
	v_mov_b32_e32 v60, v0
	v_mov_b32_e32 v61, v0
	v_mov_b32_e32 v62, v0
	v_mov_b32_e32 v63, v0
	v_mov_b32_e32 v64, v0
	v_mov_b32_e32 v65, v0
	v_mov_b32_e32 v66, v0
	v_mov_b32_e32 v67, v0
	v_mov_b32_e32 v68, v0
	v_mov_b32_e32 v69, v0
	v_mov_b32_e32 v70, v0
	v_mov_b32_e32 v71, v0
	v_mov_b32_e32 v72, v0
	v_mov_b32_e32 v73, v0
	v_mov_b32_e32 v74, v0
	v_mov_b32_e32 v75, v0
	v_mov_b32_e32 v76, v0
	v_mov_b32_e32 v77, v0
	v_mov_b32_e32 v78, v0
	v_mov_b32_e32 v79, v0
	v_mov_b32_e32 v80, v0
	v_mov_b32_e32 v81, v0
	v_mov_b32_e32 v82, v0
	v_mov_b32_e32 v83, v0
	v_mov_b32_e32 v84, v0
	v_mov_b32_e32 v85, v0
	v_mov_b32_e32 v86, v0
	v_mov_b32_e32 v87, v0
	v_mov_b32_e32 v88, v0
	v_mov_b32_e32 v89, v0
	v_mov_b32_e32 v90, v0
	v_mov_b32_e32 v91, v0
	v_mov_b32_e32 v92, v0
	v_mov_b32_e32 v93, v0
	v_mov_b32_e32 v94, v0
	v_mov_b32_e32 v95, v0
	v_mov_b32_e32 v96, v0
	v_mov_b32_e32 v97, v0
	v_mov_b32_e32 v98, v0
	v_mov_b32_e32 v99, v0
	v_mov_b32_e32 v100, v0
	v_mov_b32_e32 v101, v0
	v_mov_b32_e32 v102, v0
	v_mov_b32_e32 v103, v0
	v_mov_b32_e32 v104, v0
	v_mov_b32_e32 v105, v0
	v_mov_b32_e32 v106, v0
	v_mov_b32_e32 v107, v0
	v_mov_b32_e32 v108, v0
	v_mov_b32_e32 v109, v0
	v_mov_b32_e32 v110, v0
	v_mov_b32_e32 v111, v0
	v_mov_b32_e32 v112, v0
	v_mov_b32_e32 v113, v0
	v_mov_b32_e32 v114, v0
	v_mov_b32_e32 v115, v0
	v_mov_b32_e32 v116, v0
	v_mov_b32_e32 v117, v0
	v_mov_b32_e32 v118, v0
	v_mov_b32_e32 v119, v0
	v_mov_b32_e32 v120, v0
	v_mov_b32_e32 v121, v0
	v_mov_b32_e32 v122, v0
	v_mov_b32_e32 v123, v0
	v_mov_b32_e32 v124, v0
	v_mov_b32_e32 v125, v0
	v_mov_b32_e32 v126, v0
	v_mov_b32_e32 v127, v0
	s_barrier
	s_waitcnt vmcnt(6)
	ds_write_b128 v180, v[148:151] offset:36864
	ds_write_b128 v180, v[128:131]
	s_waitcnt vmcnt(5)
	ds_write_b128 v180, v[160:163] offset:41472
	s_waitcnt vmcnt(4)
	ds_write_b128 v180, v[168:171] offset:46080
	s_waitcnt vmcnt(3)
	ds_write_b128 v180, v[172:175] offset:50688
	ds_write_b128 v180, v[132:135] offset:4608
	ds_write_b128 v180, v[136:139] offset:9216
	ds_write_b128 v180, v[140:143] offset:13824
	ds_write_b128 v180, v[144:147] offset:18432
	s_waitcnt vmcnt(2)
	ds_write_b128 v180, v[152:155] offset:23040
	s_waitcnt vmcnt(1)
	ds_write_b128 v180, v[156:159] offset:27648
	s_waitcnt vmcnt(0)
	ds_write_b128 v180, v[164:167] offset:32256
	s_waitcnt lgkmcnt(0)
	s_barrier
	s_branch .LBB0_743

; #define MFMA32(a, b, c) __builtin_amdgcn_mfma_f32_32x32x16_bf16((a), (b), (c), 0, 0, 0)
; template <int MODE>
; DI void gemm_phase(const Params& p, int layer, char* smem, const u16* A, const u16* Bt, int Mtiles, int Ntiles, const bool dry) {
;     ...
;     for (int kt = 0; kt < 16; kt++) {
;       if (kt + 1 < 16 && !(dry && DRYVAR == 1)) GLOAD(kt + 1)
;       const u16* as = As + (wm * 128 + r) * LDS_STRIDE + h * 8;
;       const u16* bs = Bs + (wn * 64 + r) * LDS_STRIDE + h * 8;
;       if (!(dry && DRYVAR == 2)) {
;         bf16x8 af[2][4], b0, b1;
; #pragma unroll
;         for (int i = 0; i < 4; i++) af[0][i] = *(const bf16x8*)(as + i * 32 * LDS_STRIDE);
;         b0 = *(const bf16x8*)(bs); b1 = *(const bf16x8*)(bs + 32 * LDS_STRIDE);
; #pragma unroll
;         for (int kk = 0; kk < 4; kk++) {
;           const int cur = kk & 1, nxt = cur ^ 1;
;           if (kk < 3) {
; #pragma unroll
;             for (int i = 0; i < 4; i++) af[nxt][i] = *(const bf16x8*)(as + i * 32 * LDS_STRIDE + (kk + 1) * 16);
;           }
;           __builtin_amdgcn_s_setprio(1);
; #pragma unroll
;           for (int i = 0; i < 4; i++) acc[i][0] = MFMA32(af[cur][i], b0, acc[i][0]);
;           if (kk < 3) b0 = *(const bf16x8*)(bs + (kk + 1) * 16);
; #pragma unroll
;           for (int i = 0; i < 4; i++) acc[i][1] = MFMA32(af[cur][i], b1, acc[i][1]);
;           if (kk < 3) b1 = *(const bf16x8*)(bs + 32 * LDS_STRIDE + (kk + 1) * 16);
;           __builtin_amdgcn_s_setprio(0);
;         }
;       }
;       __syncthreads();
;       if (kt + 1 < 16 && !(dry && DRYVAR == 1)) LSTORE()
;       __syncthreads();
.LBB0_745:
	ds_read_b128 v[200:203], v181 offset:36864
	ds_read_b128 v[204:207], v181 offset:41472
	ds_read_b128 v[208:211], v182
	ds_read_b128 v[212:215], v182 offset:32
	ds_read_b128 v[216:219], v182 offset:4608
	ds_read_b128 v[230:233], v182 offset:4640
	ds_read_b128 v[234:237], v182 offset:9216
	ds_read_b128 v[238:241], v182 offset:9248
	ds_read_b128 v[242:245], v182 offset:13824
	ds_read_b128 v[246:249], v182 offset:13856
	s_waitcnt lgkmcnt(7)
	v_mfma_f32_32x32x16_bf16 v[112:127], v[208:211], v[200:203], v[112:127]
	s_waitcnt lgkmcnt(5)
	v_mfma_f32_32x32x16_bf16 v[80:95], v[216:219], v[200:203], v[80:95]
	s_waitcnt lgkmcnt(3)
	v_mfma_f32_32x32x16_bf16 v[48:63], v[234:237], v[200:203], v[48:63]
	s_waitcnt lgkmcnt(1)
	v_mfma_f32_32x32x16_bf16 v[16:31], v[242:245], v[200:203], v[16:31]
	v_mfma_f32_32x32x16_bf16 v[96:111], v[208:211], v[204:207], v[96:111]
	ds_read_b128 v[200:203], v181 offset:36896
	ds_read_b128 v[208:211], v181 offset:41504
	v_mfma_f32_32x32x16_bf16 v[64:79], v[216:219], v[204:207], v[64:79]
	v_mfma_f32_32x32x16_bf16 v[32:47], v[234:237], v[204:207], v[32:47]
	v_mfma_f32_32x32x16_bf16 v[0:15], v[242:245], v[204:207], v[0:15]
	ds_read_b128 v[204:207], v182 offset:64
	ds_read_b128 v[216:219], v182 offset:4672
	ds_read_b128 v[234:237], v182 offset:9280
	ds_read_b128 v[242:245], v182 offset:13888
	s_waitcnt lgkmcnt(5)
	v_mfma_f32_32x32x16_bf16 v[112:127], v[212:215], v[200:203], v[112:127]
	v_mfma_f32_32x32x16_bf16 v[80:95], v[230:233], v[200:203], v[80:95]
	v_mfma_f32_32x32x16_bf16 v[48:63], v[238:241], v[200:203], v[48:63]
	v_mfma_f32_32x32x16_bf16 v[16:31], v[246:249], v[200:203], v[16:31]
	s_waitcnt lgkmcnt(4)
	v_mfma_f32_32x32x16_bf16 v[96:111], v[212:215], v[208:211], v[96:111]
	ds_read_b128 v[200:203], v181 offset:36928
	ds_read_b128 v[212:215], v181 offset:41536
	v_mfma_f32_32x32x16_bf16 v[64:79], v[230:233], v[208:211], v[64:79]
	v_mfma_f32_32x32x16_bf16 v[32:47], v[238:241], v[208:211], v[32:47]
	v_mfma_f32_32x32x16_bf16 v[0:15], v[246:249], v[208:211], v[0:15]
	ds_read_b128 v[208:211], v182 offset:96
	ds_read_b128 v[230:233], v182 offset:4704
	ds_read_b128 v[238:241], v182 offset:9312
	ds_read_b128 v[246:249], v182 offset:13920
	s_waitcnt lgkmcnt(5)
	v_mfma_f32_32x32x16_bf16 v[112:127], v[204:207], v[200:203], v[112:127]
	v_mfma_f32_32x32x16_bf16 v[80:95], v[216:219], v[200:203], v[80:95]
	v_mfma_f32_32x32x16_bf16 v[48:63], v[234:237], v[200:203], v[48:63]
	v_mfma_f32_32x32x16_bf16 v[16:31], v[242:245], v[200:203], v[16:31]
	s_waitcnt lgkmcnt(4)
	v_mfma_f32_32x32x16_bf16 v[96:111], v[204:207], v[212:215], v[96:111]
	ds_read_b128 v[200:203], v181 offset:36960
	ds_read_b128 v[204:207], v181 offset:41568
	v_mfma_f32_32x32x16_bf16 v[64:79], v[216:219], v[212:215], v[64:79]
	v_mfma_f32_32x32x16_bf16 v[32:47], v[234:237], v[212:215], v[32:47]
	v_mfma_f32_32x32x16_bf16 v[0:15], v[242:245], v[212:215], v[0:15]
	s_waitcnt lgkmcnt(1)
	v_mfma_f32_32x32x16_bf16 v[112:127], v[208:211], v[200:203], v[112:127]
	v_mfma_f32_32x32x16_bf16 v[80:95], v[230:233], v[200:203], v[80:95]
	v_mfma_f32_32x32x16_bf16 v[48:63], v[238:241], v[200:203], v[48:63]
	v_mfma_f32_32x32x16_bf16 v[16:31], v[246:249], v[200:203], v[16:31]
	s_waitcnt lgkmcnt(0)
	v_mfma_f32_32x32x16_bf16 v[96:111], v[208:211], v[204:207], v[96:111]
	v_mfma_f32_32x32x16_bf16 v[64:79], v[230:233], v[204:207], v[64:79]
	v_mfma_f32_32x32x16_bf16 v[32:47], v[238:241], v[204:207], v[32:47]
	v_mfma_f32_32x32x16_bf16 v[0:15], v[246:249], v[204:207], v[0:15]
	s_andn2_b64 vcc, exec, s[48:49]
	s_barrier
	s_cbranch_vccnz .LBB0_742
	s_waitcnt vmcnt(11)
	ds_write_b128 v180, v[128:131]
	s_waitcnt vmcnt(10)
	ds_write_b128 v180, v[132:135] offset:4608
	s_waitcnt vmcnt(9)
	ds_write_b128 v180, v[136:139] offset:9216
	s_waitcnt vmcnt(8)
	ds_write_b128 v180, v[140:143] offset:13824
	s_waitcnt vmcnt(7)
	ds_write_b128 v180, v[144:147] offset:18432
	s_waitcnt vmcnt(6)
	ds_write_b128 v180, v[152:155] offset:23040
	s_waitcnt vmcnt(5)
	ds_write_b128 v180, v[156:159] offset:27648
	s_waitcnt vmcnt(4)
	ds_write_b128 v180, v[164:167] offset:32256
	s_waitcnt vmcnt(3)
	ds_write_b128 v180, v[148:151] offset:36864
	s_waitcnt vmcnt(2)
	ds_write_b128 v180, v[160:163] offset:41472
	s_waitcnt vmcnt(1)
	ds_write_b128 v180, v[168:171] offset:46080
	s_waitcnt vmcnt(0)
	ds_write_b128 v180, v[172:175] offset:50688
	s_branch .LBB0_742
; DI int crow(int i, int h) { return (i & 3) + 8 * (i >> 2) + 4 * h; }
; template <int MODE>
; DI void gemm_phase(const Params& p, int layer, char* smem, const u16* A, const u16* Bt, int Mtiles, int Ntiles, const bool dry) {
;     ...
;     const int m0 = mt * 256, n0 = nt * 128;
;     const int c4 = (tid & 31) * 4, rr0 = tid >> 5;
; #pragma unroll
;     for (int ph = 0; ph < 2; ph++) {
;       if (ph) __syncthreads();
; #pragma unroll
;       for (int ii = 0; ii < 2; ii++)
; #pragma unroll
;         for (int j = 0; j < 2; j++)
; #pragma unroll
;           for (int e = 0; e < 16; e++) Ct[(wm * 64 + ii * 32 + crow(e, h)) * CT_STRIDE + wn * 64 + j * 32 + r] = acc[ph * 2 + ii][j][e];
;       __syncthreads();
;       if (MODE == 1) {
;         const float4 g1 = *(const float4*)(ada_ptr(p, layer, row_batch(m0), 2) + n0 + c4);
;         float* XP = dry ? (float*)p.U : (float*)(p.S + OFF_XP);
; #pragma unroll 1
;         for (int q0 = 0; q0 < 16; q0 += 2) {
;           float4 xv[2], cv[2];
; #pragma unroll
;           for (int j = 0; j < 2; j++) {
;             const int rl = rr0 + (q0 + j) * 8, row = m0 + (rl >> 6) * 128 + ph * 64 + (rl & 63);
;             const float* xo = (layer == 0) ? ((row < NLAT) ? p.x + (size_t)row * D : p.ctx + (size_t)(row - NLAT) * D) : p.X + (size_t)row * D;
;             xv[j] = *(const float4*)(xo + n0 + c4);
;             cv[j] = *(const float4*)(Ct + rl * CT_STRIDE + c4);
.LBB0_747:
	s_setprio 0
	s_lshl_b32 s20, s38, 8
	s_min_i32 s4, s20, 0x8000
	s_ashr_i32 s4, s4, 13
	s_lshl_b32 s44, s44, 7
	s_add_i32 s4, s4, s24
	s_mul_hi_i32 s5, s4, 0x6000
	s_mulk_i32 s4, 0x6000
	s_ashr_i32 s45, s44, 31
	ds_write2_b32 v186, v112, v96 offset1:32
	ds_write2_b32 v186, v113, v97 offset0:132 offset1:164
	v_add_u32_e32 v96, 0x400, v186
	ds_write2_b32 v96, v114, v98 offset0:8 offset1:40
	ds_write2_b32 v96, v115, v99 offset0:140 offset1:172
	v_add_u32_e32 v97, 0x1000, v186
	v_add_u32_e32 v98, 0x1400, v186
	v_add_u32_e32 v99, 0x2000, v186
	s_add_u32 s21, s6, s4
	ds_write2_b32 v97, v116, v100 offset0:32 offset1:64
	ds_write2_b32 v97, v117, v101 offset0:164 offset1:196
	ds_write2_b32 v98, v118, v102 offset0:40 offset1:72
	ds_write2_b32 v98, v119, v103 offset0:172 offset1:204
	ds_write2_b32 v99, v120, v104 offset0:64 offset1:96
	ds_write2_b32 v99, v121, v105 offset0:196 offset1:228
	v_add_u32_e32 v100, 0x2400, v186
	v_add_u32_e32 v101, 0x3000, v186
	v_add_u32_e32 v102, 0x3200, v186
	v_add_u32_e32 v104, 0x3600, v186
	s_addc_u32 s27, s7, s5
	s_lshl_b64 s[4:5], s[44:45], 2
	ds_write2_b32 v100, v122, v106 offset0:72 offset1:104
	ds_write2_b32 v100, v123, v107 offset0:204 offset1:236
	ds_write2_b32 v101, v124, v108 offset0:96 offset1:128
	ds_write2_b32 v102, v125, v109 offset0:100 offset1:132
	v_add_u32_e32 v103, 0x3400, v186
	ds_write2_b32 v104, v127, v111 offset0:108 offset1:140
	v_add_u32_e32 v105, 0x4000, v186
	v_add_u32_e32 v106, 0x4400, v186
	v_add_u32_e32 v107, 0x4800, v186
	v_add_u32_e32 v108, 0x5000, v186
	v_add_u32_e32 v109, 0x5400, v186
	v_add_u32_e32 v111, 0x6000, v186
	s_add_u32 s26, s21, s4
	ds_write2_b32 v103, v126, v110 offset0:104 offset1:136
	ds_write2_b32 v105, v80, v64 offset0:128 offset1:160
	ds_write2_b32 v106, v81, v65 offset0:4 offset1:36
	ds_write2_b32 v106, v82, v66 offset0:136 offset1:168
	ds_write2_b32 v107, v83, v67 offset0:12 offset1:44
	ds_write2_b32 v108, v84, v68 offset0:160 offset1:192
	ds_write2_b32 v109, v85, v69 offset0:36 offset1:68
	ds_write2_b32 v109, v86, v70 offset0:168 offset1:200
	v_add_u32_e32 v110, 0x5800, v186
	ds_write2_b32 v111, v88, v72 offset0:192 offset1:224
	v_add_u32_e32 v88, 0x6400, v186
	s_addc_u32 s27, s27, s5
	v_lshlrev_b32_e32 v196, 2, v184
	ds_write2_b32 v110, v87, v71 offset0:44 offset1:76
	ds_write2_b32 v88, v89, v73 offset0:68 offset1:100
	ds_write2_b32 v88, v90, v74 offset0:200 offset1:232
	v_add_u32_e32 v89, 0x6800, v186
	v_lshl_add_u64 v[68:69], s[26:27], 0, v[196:197]
	ds_write2_b32 v89, v91, v75 offset0:76 offset1:108
	v_add_u32_e32 v90, 0x7200, v186
	v_add_u32_e32 v91, 0x7400, v186
	v_add_co_u32_e32 v64, vcc, 0x2000, v68
	ds_write2_b32 v90, v92, v76 offset0:96 offset1:128
	ds_write2_b32 v91, v93, v77 offset0:100 offset1:132
	v_add_u32_e32 v92, 0x7600, v186
	v_add_u32_e32 v93, 0x7800, v186
	v_addc_co_u32_e32 v65, vcc, 0, v69, vcc
	ds_write2_b32 v92, v94, v78 offset0:104 offset1:136
	ds_write2_b32 v93, v95, v79 offset0:108 offset1:140
	s_waitcnt lgkmcnt(0)
	s_barrier
	global_load_dwordx4 v[64:67], v[64:65], off
	s_mov_b64 s[26:27], 0x2000
	v_lshl_add_u64 v[78:79], v[68:69], 0, s[26:27]
	v_lshl_add_u64 v[76:77], v[188:189], 0, s[4:5]
	s_mov_b32 s30, -2
	v_mov_b32_e32 v94, v187
	v_mov_b32_e32 v95, v183
	v_mov_b32_e32 v112, v185
	s_branch .LBB0_750

; template <int MODE>
; DI void gemm_phase(const Params& p, int layer, char* smem, const u16* A, const u16* Bt, int Mtiles, int Ntiles, const bool dry) {
;     ...
;   for (int ch = xcd; ch < nchunks; ch += 8)
;   for (int jj = jx; jj < 64; jj += wpx) {
;     const int L = ch * 64 + jj;
;     if (L >= ntiles) continue;
;     const int mt = (L / (4 * Ntiles)) * 4 + (L & 3), nt = (L >> 2) % Ntiles;
;     const u16* Ag = A + ((size_t)mt * 256 + srow) * D + sc8;
;     const u16* Bg = Bt + ((size_t)nt * 128 + srow) * D + sc8;
;     f32x16 acc[4][2];
; #pragma unroll
;     for (int i = 0; i < 4; i++)
; #pragma unroll
;       for (int j = 0; j < 2; j++)
; #pragma unroll
;         for (int e = 0; e < 16; e++) acc[i][j][e] = 0.f;
;     bf16x8 ra0, ra1, ra2, ra3, ra4, ra5, ra6, ra7, rb0, rb1, rb2, rb3;
;     ...
;     GLOAD(0)
;     __syncthreads();
;     LSTORE()
;     __syncthreads();
.LBB0_932:
	s_add_i32 s20, s48, s36
	s_ashr_i32 s21, s20, 31
	s_lshr_b32 s26, s21, 26
	s_add_i32 s26, s20, s26
	s_ashr_i32 s26, s26, 6
	s_lshl_b32 s26, s26, 2
	s_and_b32 s27, s48, 3
	s_ashr_i32 s20, s20, 2
	s_lshr_b32 s21, s21, 28
	s_or_b32 s40, s26, s27
	s_add_i32 s21, s20, s21
	s_and_b32 s21, s21, -16
	s_ashr_i32 s41, s40, 31
	s_sub_i32 s42, s20, s21
	s_cmp_ge_u32 s74, 0x100
	s_cbranch_scc0 .Lprio_skip_1
	s_setprio 1
.Lprio_skip_1:
	s_lshl_b64 s[20:21], s[40:41], 19
	v_lshl_add_u64 v[0:1], v[176:177], 0, s[20:21]
	v_add_co_u32_e32 v4, vcc, s91, v0
	global_load_dwordx4 v[128:131], v[0:1], off
	s_nop 0
	v_addc_co_u32_e32 v5, vcc, 0, v1, vcc
	v_add_co_u32_e32 v6, vcc, s89, v0
	s_ashr_i32 s43, s42, 31
	s_nop 0
	v_addc_co_u32_e32 v7, vcc, 0, v1, vcc
	global_load_dwordx4 v[132:135], v[4:5], off
	global_load_dwordx4 v[136:139], v[6:7], off
	v_add_co_u32_e32 v4, vcc, s23, v0
	s_lshl_b64 s[44:45], s[42:43], 18
	s_nop 0
	v_addc_co_u32_e32 v5, vcc, 0, v1, vcc
	v_add_co_u32_e32 v6, vcc, s49, v0
	v_lshl_add_u64 v[2:3], v[178:179], 0, s[44:45]
	s_nop 0
	v_addc_co_u32_e32 v7, vcc, 0, v1, vcc
	global_load_dwordx4 v[140:143], v[4:5], off
	global_load_dwordx4 v[144:147], v[6:7], off
	v_add_co_u32_e32 v4, vcc, s50, v0
	global_load_dwordx4 v[148:151], v[2:3], off
	s_nop 0
	v_addc_co_u32_e32 v5, vcc, 0, v1, vcc
	v_add_co_u32_e32 v6, vcc, s51, v0
	s_mov_b32 s20, 0x70000
	s_nop 0
	v_addc_co_u32_e32 v7, vcc, 0, v1, vcc
	v_add_co_u32_e32 v8, vcc, s91, v2
	v_lshl_add_u64 v[194:195], v[190:191], 0, s[44:45]
	s_nop 0
	v_addc_co_u32_e32 v9, vcc, 0, v3, vcc
	v_add_co_u32_e32 v10, vcc, s89, v2
	s_mov_b64 s[44:45], 0
	s_nop 0
	v_addc_co_u32_e32 v11, vcc, 0, v3, vcc
	v_add_co_u32_e32 v2, vcc, s23, v2
	global_load_dwordx4 v[160:163], v[8:9], off
	global_load_dwordx4 v[168:171], v[10:11], off
	v_addc_co_u32_e32 v3, vcc, 0, v3, vcc
	v_add_co_u32_e32 v0, vcc, s20, v0
	global_load_dwordx4 v[172:175], v[2:3], off
	global_load_dwordx4 v[152:155], v[4:5], off
	global_load_dwordx4 v[156:159], v[6:7], off
	v_addc_co_u32_e32 v1, vcc, 0, v1, vcc
	global_load_dwordx4 v[164:167], v[0:1], off
	s_and_b32 s20, s37, 3
	s_or_b32 s20, s26, s20
	s_ashr_i32 s21, s20, 31
	s_lshl_b64 s[20:21], s[20:21], 19
	v_mov_b32_e32 v0, 0
	v_lshl_add_u64 v[192:193], v[188:189], 0, s[20:21]
	v_mov_b32_e32 v1, v0
	v_mov_b32_e32 v2, v0
	v_mov_b32_e32 v3, v0
	v_mov_b32_e32 v4, v0
	v_mov_b32_e32 v5, v0
	v_mov_b32_e32 v6, v0
	v_mov_b32_e32 v7, v0
	v_mov_b32_e32 v8, v0
	v_mov_b32_e32 v9, v0
	v_mov_b32_e32 v10, v0
	v_mov_b32_e32 v11, v0
	s_waitcnt vmcnt(12)
	v_mov_b32_e32 v12, v0
	v_mov_b32_e32 v13, v0
	v_mov_b32_e32 v14, v0
	v_mov_b32_e32 v15, v0
	v_mov_b32_e32 v16, v0
	v_mov_b32_e32 v17, v0
	v_mov_b32_e32 v18, v0
	v_mov_b32_e32 v19, v0
	v_mov_b32_e32 v20, v0
	v_mov_b32_e32 v21, v0
	v_mov_b32_e32 v22, v0
	v_mov_b32_e32 v23, v0
	v_mov_b32_e32 v24, v0
	v_mov_b32_e32 v25, v0
	v_mov_b32_e32 v26, v0
	v_mov_b32_e32 v27, v0
	v_mov_b32_e32 v28, v0
	v_mov_b32_e32 v29, v0
	v_mov_b32_e32 v30, v0
	v_mov_b32_e32 v31, v0
	v_mov_b32_e32 v32, v0
	v_mov_b32_e32 v33, v0
	v_mov_b32_e32 v34, v0
	v_mov_b32_e32 v35, v0
	v_mov_b32_e32 v36, v0
	v_mov_b32_e32 v37, v0
	v_mov_b32_e32 v38, v0
	v_mov_b32_e32 v39, v0
	v_mov_b32_e32 v40, v0
	v_mov_b32_e32 v41, v0
	v_mov_b32_e32 v42, v0
	v_mov_b32_e32 v43, v0
	v_mov_b32_e32 v44, v0
	v_mov_b32_e32 v45, v0
	v_mov_b32_e32 v46, v0
	v_mov_b32_e32 v47, v0
	v_mov_b32_e32 v48, v0
	v_mov_b32_e32 v49, v0
	v_mov_b32_e32 v50, v0
	v_mov_b32_e32 v51, v0
	v_mov_b32_e32 v52, v0
	v_mov_b32_e32 v53, v0
	v_mov_b32_e32 v54, v0
	v_mov_b32_e32 v55, v0
	v_mov_b32_e32 v56, v0
	v_mov_b32_e32 v57, v0
	v_mov_b32_e32 v58, v0
	v_mov_b32_e32 v59, v0
	v_mov_b32_e32 v60, v0
	v_mov_b32_e32 v61, v0
	v_mov_b32_e32 v62, v0
	v_mov_b32_e32 v63, v0
	v_mov_b32_e32 v64, v0
	v_mov_b32_e32 v65, v0
	v_mov_b32_e32 v66, v0
	v_mov_b32_e32 v67, v0
	v_mov_b32_e32 v68, v0
	v_mov_b32_e32 v69, v0
	v_mov_b32_e32 v70, v0
	v_mov_b32_e32 v71, v0
	v_mov_b32_e32 v72, v0
	v_mov_b32_e32 v73, v0
	v_mov_b32_e32 v74, v0
	v_mov_b32_e32 v75, v0
	v_mov_b32_e32 v76, v0
	v_mov_b32_e32 v77, v0
	v_mov_b32_e32 v78, v0
	v_mov_b32_e32 v79, v0
	v_mov_b32_e32 v80, v0
	v_mov_b32_e32 v81, v0
	v_mov_b32_e32 v82, v0
	v_mov_b32_e32 v83, v0
	v_mov_b32_e32 v84, v0
	v_mov_b32_e32 v85, v0
	v_mov_b32_e32 v86, v0
	v_mov_b32_e32 v87, v0
	v_mov_b32_e32 v88, v0
	v_mov_b32_e32 v89, v0
	v_mov_b32_e32 v90, v0
	v_mov_b32_e32 v91, v0
	v_mov_b32_e32 v92, v0
	v_mov_b32_e32 v93, v0
	v_mov_b32_e32 v94, v0
	v_mov_b32_e32 v95, v0
	v_mov_b32_e32 v96, v0
	v_mov_b32_e32 v97, v0
	v_mov_b32_e32 v98, v0
	v_mov_b32_e32 v99, v0
	v_mov_b32_e32 v100, v0
	v_mov_b32_e32 v101, v0
	v_mov_b32_e32 v102, v0
	v_mov_b32_e32 v103, v0
	v_mov_b32_e32 v104, v0
	v_mov_b32_e32 v105, v0
	v_mov_b32_e32 v106, v0
	v_mov_b32_e32 v107, v0
	v_mov_b32_e32 v108, v0
	v_mov_b32_e32 v109, v0
	v_mov_b32_e32 v110, v0
	v_mov_b32_e32 v111, v0
	v_mov_b32_e32 v112, v0
	v_mov_b32_e32 v113, v0
	v_mov_b32_e32 v114, v0
	v_mov_b32_e32 v115, v0
	v_mov_b32_e32 v116, v0
	v_mov_b32_e32 v117, v0
	v_mov_b32_e32 v118, v0
	v_mov_b32_e32 v119, v0
	v_mov_b32_e32 v120, v0
	v_mov_b32_e32 v121, v0
	v_mov_b32_e32 v122, v0
	v_mov_b32_e32 v123, v0
	v_mov_b32_e32 v124, v0
	v_mov_b32_e32 v125, v0
	v_mov_b32_e32 v126, v0
	v_mov_b32_e32 v127, v0
	s_barrier
	s_waitcnt vmcnt(6)
	ds_write_b128 v180, v[148:151] offset:36864
	ds_write_b128 v180, v[128:131]
	s_waitcnt vmcnt(5)
	ds_write_b128 v180, v[160:163] offset:41472
	s_waitcnt vmcnt(4)
	ds_write_b128 v180, v[168:171] offset:46080
	s_waitcnt vmcnt(3)
	ds_write_b128 v180, v[172:175] offset:50688
	ds_write_b128 v180, v[132:135] offset:4608
	ds_write_b128 v180, v[136:139] offset:9216
	ds_write_b128 v180, v[140:143] offset:13824
	ds_write_b128 v180, v[144:147] offset:18432
	s_waitcnt vmcnt(2)
	ds_write_b128 v180, v[152:155] offset:23040
	s_waitcnt vmcnt(1)
	ds_write_b128 v180, v[156:159] offset:27648
	s_waitcnt vmcnt(0)
	ds_write_b128 v180, v[164:167] offset:32256
	s_waitcnt lgkmcnt(0)
	s_barrier
	s_branch .LBB0_934

; DI int crow(int i, int h) { return (i & 3) + 8 * (i >> 2) + 4 * h; }
; #define MFMA32(a, b, c) __builtin_amdgcn_mfma_f32_32x32x16_bf16((a), (b), (c), 0, 0, 0)
; template <int MODE>
; DI void gemm_phase(const Params& p, int layer, char* smem, const u16* A, const u16* Bt, int Mtiles, int Ntiles, const bool dry) {
;     ...
;     for (int kt = 0; kt < 16; kt++) {
;       if (kt + 1 < 16 && !(dry && DRYVAR == 1)) GLOAD(kt + 1)
;       const u16* as = As + (wm * 128 + r) * LDS_STRIDE + h * 8;
;       const u16* bs = Bs + (wn * 64 + r) * LDS_STRIDE + h * 8;
;       if (!(dry && DRYVAR == 2)) {
;         bf16x8 af[2][4], b0, b1;
; #pragma unroll
;         for (int i = 0; i < 4; i++) af[0][i] = *(const bf16x8*)(as + i * 32 * LDS_STRIDE);
;         b0 = *(const bf16x8*)(bs); b1 = *(const bf16x8*)(bs + 32 * LDS_STRIDE);
; #pragma unroll
;         for (int kk = 0; kk < 4; kk++) {
;           const int cur = kk & 1, nxt = cur ^ 1;
;           if (kk < 3) {
; #pragma unroll
;             for (int i = 0; i < 4; i++) af[nxt][i] = *(const bf16x8*)(as + i * 32 * LDS_STRIDE + (kk + 1) * 16);
;           }
;           __builtin_amdgcn_s_setprio(1);
; #pragma unroll
;           for (int i = 0; i < 4; i++) acc[i][0] = MFMA32(af[cur][i], b0, acc[i][0]);
;           if (kk < 3) b0 = *(const bf16x8*)(bs + (kk + 1) * 16);
; #pragma unroll
;           for (int i = 0; i < 4; i++) acc[i][1] = MFMA32(af[cur][i], b1, acc[i][1]);
;           if (kk < 3) b1 = *(const bf16x8*)(bs + 32 * LDS_STRIDE + (kk + 1) * 16);
;           __builtin_amdgcn_s_setprio(0);
;         }
;       }
;       __syncthreads();
;       if (kt + 1 < 16 && !(dry && DRYVAR == 1)) LSTORE()
;       __syncthreads();
;     }
;     ...
;     const int m0 = mt * 256, n0 = nt * 128;
;     const int c4 = (tid & 31) * 4, rr0 = tid >> 5;
; #pragma unroll
;     for (int ph = 0; ph < 2; ph++) {
;       if (ph) __syncthreads();
; #pragma unroll
;       for (int ii = 0; ii < 2; ii++)
; #pragma unroll
;         for (int j = 0; j < 2; j++)
; #pragma unroll
;           for (int e = 0; e < 16; e++) Ct[(wm * 64 + ii * 32 + crow(e, h)) * CT_STRIDE + wn * 64 + j * 32 + r] = acc[ph * 2 + ii][j][e];
.LBB0_936:
	ds_read_b128 v[198:201], v181 offset:36864
	ds_read_b128 v[202:205], v181 offset:41472
	ds_read_b128 v[206:209], v182
	ds_read_b128 v[210:213], v182 offset:32
	ds_read_b128 v[214:217], v182 offset:4608
	ds_read_b128 v[230:233], v182 offset:4640
	ds_read_b128 v[234:237], v182 offset:9216
	ds_read_b128 v[238:241], v182 offset:9248
	ds_read_b128 v[242:245], v182 offset:13824
	ds_read_b128 v[246:249], v182 offset:13856
	s_waitcnt lgkmcnt(7)
	v_mfma_f32_32x32x16_bf16 v[112:127], v[206:209], v[198:201], v[112:127]
	s_waitcnt lgkmcnt(5)
	v_mfma_f32_32x32x16_bf16 v[80:95], v[214:217], v[198:201], v[80:95]
	s_waitcnt lgkmcnt(3)
	v_mfma_f32_32x32x16_bf16 v[48:63], v[234:237], v[198:201], v[48:63]
	s_waitcnt lgkmcnt(1)
	v_mfma_f32_32x32x16_bf16 v[16:31], v[242:245], v[198:201], v[16:31]
	v_mfma_f32_32x32x16_bf16 v[96:111], v[206:209], v[202:205], v[96:111]
	ds_read_b128 v[198:201], v181 offset:36896
	ds_read_b128 v[206:209], v181 offset:41504
	v_mfma_f32_32x32x16_bf16 v[64:79], v[214:217], v[202:205], v[64:79]
	v_mfma_f32_32x32x16_bf16 v[32:47], v[234:237], v[202:205], v[32:47]
	v_mfma_f32_32x32x16_bf16 v[0:15], v[242:245], v[202:205], v[0:15]
	ds_read_b128 v[202:205], v182 offset:64
	ds_read_b128 v[214:217], v182 offset:4672
	ds_read_b128 v[234:237], v182 offset:9280
	ds_read_b128 v[242:245], v182 offset:13888
	s_waitcnt lgkmcnt(5)
	v_mfma_f32_32x32x16_bf16 v[112:127], v[210:213], v[198:201], v[112:127]
	v_mfma_f32_32x32x16_bf16 v[80:95], v[230:233], v[198:201], v[80:95]
	v_mfma_f32_32x32x16_bf16 v[48:63], v[238:241], v[198:201], v[48:63]
	v_mfma_f32_32x32x16_bf16 v[16:31], v[246:249], v[198:201], v[16:31]
	s_waitcnt lgkmcnt(4)
	v_mfma_f32_32x32x16_bf16 v[96:111], v[210:213], v[206:209], v[96:111]
	ds_read_b128 v[198:201], v181 offset:36928
	ds_read_b128 v[210:213], v181 offset:41536
	v_mfma_f32_32x32x16_bf16 v[64:79], v[230:233], v[206:209], v[64:79]
	v_mfma_f32_32x32x16_bf16 v[32:47], v[238:241], v[206:209], v[32:47]
	v_mfma_f32_32x32x16_bf16 v[0:15], v[246:249], v[206:209], v[0:15]
	ds_read_b128 v[206:209], v182 offset:96
	ds_read_b128 v[230:233], v182 offset:4704
	ds_read_b128 v[238:241], v182 offset:9312
	ds_read_b128 v[246:249], v182 offset:13920
	s_waitcnt lgkmcnt(5)
	v_mfma_f32_32x32x16_bf16 v[112:127], v[202:205], v[198:201], v[112:127]
	v_mfma_f32_32x32x16_bf16 v[80:95], v[214:217], v[198:201], v[80:95]
	v_mfma_f32_32x32x16_bf16 v[48:63], v[234:237], v[198:201], v[48:63]
	v_mfma_f32_32x32x16_bf16 v[16:31], v[242:245], v[198:201], v[16:31]
	s_waitcnt lgkmcnt(4)
	v_mfma_f32_32x32x16_bf16 v[96:111], v[202:205], v[210:213], v[96:111]
	ds_read_b128 v[198:201], v181 offset:36960
	ds_read_b128 v[202:205], v181 offset:41568
	v_mfma_f32_32x32x16_bf16 v[64:79], v[214:217], v[210:213], v[64:79]
	v_mfma_f32_32x32x16_bf16 v[32:47], v[234:237], v[210:213], v[32:47]
	v_mfma_f32_32x32x16_bf16 v[0:15], v[242:245], v[210:213], v[0:15]
	s_waitcnt lgkmcnt(1)
	v_mfma_f32_32x32x16_bf16 v[112:127], v[206:209], v[198:201], v[112:127]
	v_mfma_f32_32x32x16_bf16 v[80:95], v[230:233], v[198:201], v[80:95]
	v_mfma_f32_32x32x16_bf16 v[48:63], v[238:241], v[198:201], v[48:63]
	v_mfma_f32_32x32x16_bf16 v[16:31], v[246:249], v[198:201], v[16:31]
	s_waitcnt lgkmcnt(0)
	v_mfma_f32_32x32x16_bf16 v[96:111], v[206:209], v[202:205], v[96:111]
	v_mfma_f32_32x32x16_bf16 v[64:79], v[230:233], v[202:205], v[64:79]
	v_mfma_f32_32x32x16_bf16 v[32:47], v[238:241], v[202:205], v[32:47]
	v_mfma_f32_32x32x16_bf16 v[0:15], v[246:249], v[202:205], v[0:15]
	s_andn2_b64 vcc, exec, s[46:47]
	s_barrier
	s_cbranch_vccnz .LBB0_933
	s_waitcnt vmcnt(11)
	ds_write_b128 v180, v[128:131]
	s_waitcnt vmcnt(10)
	ds_write_b128 v180, v[132:135] offset:4608
	s_waitcnt vmcnt(9)
	ds_write_b128 v180, v[136:139] offset:9216
	s_waitcnt vmcnt(8)
	ds_write_b128 v180, v[140:143] offset:13824
	s_waitcnt vmcnt(7)
	ds_write_b128 v180, v[144:147] offset:18432
	s_waitcnt vmcnt(6)
	ds_write_b128 v180, v[152:155] offset:23040
	s_waitcnt vmcnt(5)
	ds_write_b128 v180, v[156:159] offset:27648
	s_waitcnt vmcnt(4)
	ds_write_b128 v180, v[164:167] offset:32256
	s_waitcnt vmcnt(3)
	ds_write_b128 v180, v[148:151] offset:36864
	s_waitcnt vmcnt(2)
	ds_write_b128 v180, v[160:163] offset:41472
	s_waitcnt vmcnt(1)
	ds_write_b128 v180, v[168:171] offset:46080
	s_waitcnt vmcnt(0)
	ds_write_b128 v180, v[172:175] offset:50688
	s_branch .LBB0_933
.LBB0_938:
	s_setprio 0
	ds_write2_b32 v184, v112, v96 offset1:32
	ds_write2_b32 v184, v113, v97 offset0:132 offset1:164
	v_add_u32_e32 v96, 0x400, v184
	ds_write2_b32 v96, v114, v98 offset0:8 offset1:40
	ds_write2_b32 v96, v115, v99 offset0:140 offset1:172
	v_add_u32_e32 v97, 0x1000, v184
	v_add_u32_e32 v98, 0x1400, v184
	v_add_u32_e32 v99, 0x2000, v184
	ds_write2_b32 v97, v116, v100 offset0:32 offset1:64
	ds_write2_b32 v97, v117, v101 offset0:164 offset1:196
	ds_write2_b32 v98, v118, v102 offset0:40 offset1:72
	ds_write2_b32 v98, v119, v103 offset0:172 offset1:204
	ds_write2_b32 v99, v120, v104 offset0:64 offset1:96
	ds_write2_b32 v99, v121, v105 offset0:196 offset1:228
	v_add_u32_e32 v100, 0x2400, v184
	v_add_u32_e32 v105, 0x4000, v184
	ds_write2_b32 v100, v122, v106 offset0:72 offset1:104
	ds_write2_b32 v100, v123, v107 offset0:204 offset1:236
	v_add_u32_e32 v101, 0x3000, v184
	v_add_u32_e32 v102, 0x3200, v184
	v_add_u32_e32 v103, 0x3400, v184
	v_add_u32_e32 v104, 0x3600, v184
	ds_write2_b32 v105, v80, v64 offset0:128 offset1:160
	v_add_u32_e32 v80, 0x4400, v184
	ds_write2_b32 v101, v124, v108 offset0:96 offset1:128
	ds_write2_b32 v102, v125, v109 offset0:100 offset1:132
	ds_write2_b32 v103, v126, v110 offset0:104 offset1:136
	ds_write2_b32 v104, v127, v111 offset0:108 offset1:140
	ds_write2_b32 v80, v81, v65 offset0:4 offset1:36
	ds_write2_b32 v80, v82, v66 offset0:136 offset1:168
	v_add_u32_e32 v66, 0x4800, v184
	ds_write2_b32 v66, v83, v67 offset0:12 offset1:44
	v_add_u32_e32 v67, 0x5000, v184
	ds_write2_b32 v67, v84, v68 offset0:160 offset1:192
	v_add_u32_e32 v68, 0x5400, v184
	ds_write2_b32 v68, v85, v69 offset0:36 offset1:68
	ds_write2_b32 v68, v86, v70 offset0:168 offset1:200
	v_add_u32_e32 v69, 0x5800, v184
	v_add_u32_e32 v70, 0x6000, v184
	s_lshl_b32 s26, s42, 7
	ds_write2_b32 v69, v87, v71 offset0:44 offset1:76
	ds_write2_b32 v70, v88, v72 offset0:192 offset1:224
	v_add_u32_e32 v71, 0x6400, v184
	v_add_u32_e32 v72, 0x6800, v184
	s_ashr_i32 s27, s26, 31
	ds_write2_b32 v71, v89, v73 offset0:68 offset1:100
	ds_write2_b32 v71, v90, v74 offset0:200 offset1:232
	ds_write2_b32 v72, v91, v75 offset0:76 offset1:108
	v_add_u32_e32 v73, 0x7200, v184
	v_add_u32_e32 v74, 0x7400, v184
	v_add_u32_e32 v75, 0x7600, v184
	s_lshl_b32 s20, s40, 8
	ds_write2_b32 v73, v92, v76 offset0:96 offset1:128
	ds_write2_b32 v74, v93, v77 offset0:100 offset1:132
	ds_write2_b32 v75, v94, v78 offset0:104 offset1:136
	v_add_u32_e32 v76, 0x7800, v184
	v_lshl_add_u64 v[64:65], s[26:27], 1, v[186:187]
	s_mov_b32 s30, 0
	v_mov_b32_e32 v77, v196
	v_mov_b32_e32 v78, v183
	ds_write2_b32 v76, v95, v79 offset0:108 offset1:140
	s_waitcnt lgkmcnt(0)
	s_barrier

; DI int otid() { int t = threadIdx.x; asm volatile("" : "+v"(t)); return t; }
; DI int obid() { int t = blockIdx.x; asm volatile("" : "+s"(t)); return t; }
; DI void expert_epilogue(const Params& p, int layer, int nrows) {
;   const int tid = otid(), wave = tid >> 6, lane = tid & 63, g = lane >> 5, s = lane & 31;
;   const bool last = (layer == DEPTH - 1);
;   const u16* Y = (const u16*)((const char*)p.U + (size_t)NROW * 2048 * 2);
;   for (int tk = obid() * 4 + wave; tk < nrows; tk += gridDim.x * 4) {
;     const int b = row_batch(tk);
;     const int col = (g * 32 + s) * 16;
;     const float* g2 = ada_ptr(p, layer, b, 5) + col;
;     const float* gm = p.ln_gamma + (size_t)(layer * 2 + 1) * D + col;
;     const float* bt = p.ln_beta + (size_t)(layer * 2 + 1) * D + col;
;     const float* XP = (const float*)(p.S + OFF_XP) + (size_t)tk * D + col;
;     ...
;     float4 gmq[4], btq[4];
; #pragma unroll
;     for (int j4 = 0; j4 < 4; j4++) { gmq[j4] = *(const float4*)(gm + j4 * 4); btq[j4] = *(const float4*)(bt + j4 * 4); }
.LBB0_1207:
	s_waitcnt vmcnt(3) lgkmcnt(0)
	v_mov_b32_e32 v0, v220
	s_mov_b32 s0, s74
	v_ashrrev_i32_e32 v1, 6, v0
	s_nop 0
	v_lshl_add_u32 v32, s0, 2, v1
	v_cmp_gt_i32_e32 vcc, s54, v32
	s_and_saveexec_b64 s[38:39], vcc
	s_cbranch_execz .LBB0_1212
	v_lshlrev_b32_e32 v0, 4, v0
	v_and_b32_e32 v34, 0x3f0, v0
	v_and_b32_e32 v0, 64, v226
	v_add_u32_e32 v0, 64, v0
	v_xor_b32_e32 v1, 32, v226
	v_cmp_lt_i32_e32 vcc, v1, v0
	v_readlane_b32 s0, v250, 1
	s_lshl_b32 s0, s0, 11
	v_cndmask_b32_e32 v1, v226, v1, vcc
	v_lshlrev_b32_e32 v35, 2, v1
	v_xor_b32_e32 v1, 16, v226
	v_cmp_lt_i32_e32 vcc, v1, v0
	v_readlane_b32 s4, v251, 62
	s_or_b32 s24, s0, 0x400
	v_cndmask_b32_e32 v1, v226, v1, vcc
	s_waitcnt vmcnt(2)
	v_lshlrev_b32_e32 v54, 2, v1
	v_xor_b32_e32 v1, 8, v226
	v_cmp_lt_i32_e32 vcc, v1, v0
	v_lshlrev_b32_e32 v196, 1, v34
	v_readlane_b32 s5, v251, 63
	v_cndmask_b32_e32 v1, v226, v1, vcc
	v_lshlrev_b32_e32 v55, 2, v1
	v_xor_b32_e32 v1, 4, v226
	v_cmp_lt_i32_e32 vcc, v1, v0
	v_readlane_b32 s56, v252, 4
	v_lshl_add_u64 v[36:37], s[4:5], 0, v[196:197]
	v_cndmask_b32_e32 v1, v226, v1, vcc
	v_lshlrev_b32_e32 v56, 2, v1
	v_xor_b32_e32 v1, 2, v226
	v_cmp_lt_i32_e32 vcc, v1, v0
	s_lshl_b64 s[4:5], s[24:25], 2
	v_readlane_b32 s66, v252, 14
	v_cndmask_b32_e32 v1, v226, v1, vcc
	v_lshlrev_b32_e32 v57, 2, v1
	v_xor_b32_e32 v1, 1, v226
	v_readlane_b32 s67, v252, 15
	s_add_u32 s20, s66, s4
	v_cmp_lt_i32_e32 vcc, v1, v0
	v_readlane_b32 s68, v252, 16
	s_addc_u32 s21, s67, s5
	v_cndmask_b32_e32 v0, v226, v1, vcc
	s_mov_b32 s1, s25
	v_readlane_b32 s69, v252, 17
	s_add_u32 s4, s68, s4
	v_lshlrev_b32_e32 v58, 2, v0
	s_addc_u32 s5, s69, s5
	v_lshlrev_b32_e32 v0, 2, v34
	v_mov_b32_e32 v1, v197
	s_lshl_b64 s[0:1], s[0:1], 2
	v_lshl_add_u64 v[40:41], s[20:21], 0, v[0:1]
	s_add_u32 s20, s66, s0
	s_addc_u32 s21, s67, s1
	s_add_u32 s0, s68, s0
	s_addc_u32 s1, s69, s1
	v_readlane_b32 s57, v252, 5
	v_readlane_b32 s58, v252, 6
	v_readlane_b32 s59, v252, 7
	v_readlane_b32 s60, v252, 8
	v_readlane_b32 s61, v252, 9
	v_readlane_b32 s62, v252, 10
	v_readlane_b32 s63, v252, 11
	v_readlane_b32 s64, v252, 12
	v_readlane_b32 s65, v252, 13
	v_readlane_b32 s70, v252, 18
	v_readlane_b32 s71, v252, 19
	v_lshl_add_u64 v[44:45], s[0:1], 0, v[0:1]
	v_readlane_b32 s0, v250, 17
	v_readlane_b32 s1, v250, 18
	v_readlane_b32 s56, v252, 20
	s_and_b64 s[0:1], s[0:1], exec
	v_readlane_b32 s62, v252, 26
	v_readlane_b32 s63, v252, 27
	s_cselect_b32 s1, s63, s9
	s_cselect_b32 s0, s62, s8
	v_lshl_add_u64 v[38:39], s[16:17], 0, v[0:1]
	v_lshl_add_u64 v[42:43], s[20:21], 0, v[0:1]
	s_movk_i32 s20, 0x6000
	v_lshl_add_u64 v[46:47], s[4:5], 0, v[0:1]
	global_load_dwordx4 v[128:131], v[40:41], off offset:48
	global_load_dwordx4 v[124:127], v[40:41], off offset:32
	global_load_dwordx4 v[120:123], v[40:41], off offset:16
	global_load_dwordx4 v[116:119], v[40:41], off
	global_load_dwordx4 v[132:135], v[46:47], off offset:48
	global_load_dwordx4 v[136:139], v[46:47], off offset:32
	global_load_dwordx4 v[140:143], v[46:47], off offset:16
	global_load_dwordx4 v[144:147], v[46:47], off
	v_lshl_add_u64 v[48:49], s[0:1], 0, v[0:1]
	v_lshl_add_u64 v[50:51], s[10:11], 0, v[196:197]
	s_mov_b64 s[36:37], 0
	v_readlane_b32 s57, v252, 21
	v_readlane_b32 s58, v252, 22
	v_readlane_b32 s59, v252, 23
	v_readlane_b32 s60, v252, 24
	v_readlane_b32 s61, v252, 25
	v_readlane_b32 s64, v252, 28
	v_readlane_b32 s65, v252, 29
	v_readlane_b32 s66, v252, 30
	v_readlane_b32 s67, v252, 31
	v_readlane_b32 s68, v252, 32
	v_readlane_b32 s69, v252, 33
	v_readlane_b32 s70, v252, 34
	v_readlane_b32 s71, v252, 35
	s_branch .LBB0_1210

; DI void expert_epilogue(const Params& p, int layer, int nrows) {
;     ...
;     const float* XP = (const float*)(p.S + OFF_XP) + (size_t)tk * D + col;
;     float xin[16];
;     {
;       float s0 = 0.f;
; #pragma unroll
;       for (int j4 = 0; j4 < 4; j4++) {
;         const float4 t4 = *(const float4*)(XP + j4 * 4);
;         xin[j4 * 4] = t4.x; xin[j4 * 4 + 1] = t4.y; xin[j4 * 4 + 2] = t4.z; xin[j4 * 4 + 3] = t4.w;
;         s0 += t4.x + t4.y + t4.z + t4.w;
;       }
;       const float m0 = wave_sum(s0) * (1.f / D);
;       float q0 = 0.f;
; #pragma unroll
;       for (int j = 0; j < 16; j++) { xin[j] -= m0; q0 += xin[j] * xin[j]; }
;       const float r0 = rsqrtf(wave_sum(q0) * (1.f / D) + EPS);
;       const float* gm0 = p.ln_gamma + (size_t)(layer * 2 + 0) * D + col;
;       const float* bt0 = p.ln_beta + (size_t)(layer * 2 + 0) * D + col;
; #pragma unroll
;       for (int j4 = 0; j4 < 4; j4++) {
;         const float4 ga = *(const float4*)(gm0 + j4 * 4), be = *(const float4*)(bt0 + j4 * 4);
;         xin[j4 * 4] = xin[j4 * 4] * r0 * ga.x + be.x; xin[j4 * 4 + 1] = xin[j4 * 4 + 1] * r0 * ga.y + be.y;
;         xin[j4 * 4 + 2] = xin[j4 * 4 + 2] * r0 * ga.z + be.z; xin[j4 * 4 + 3] = xin[j4 * 4 + 3] * r0 * ga.w + be.w;
;       }
;     }
;     float xv[16];
;     float sum = 0.f;
;     const uint4 yq0 = *(const uint4*)(Y + (size_t)tk * D + col), yq1 = *(const uint4*)(Y + (size_t)tk * D + col + 8);
;     const u32 yw[8] = {yq0.x, yq0.y, yq0.z, yq0.w, yq1.x, yq1.y, yq1.z, yq1.w};
; #pragma unroll
;     for (int j4 = 0; j4 < 4; j4++) {
;       const float4 xo = make_float4(xin[j4 * 4], xin[j4 * 4 + 1], xin[j4 * 4 + 2], xin[j4 * 4 + 3]);
;       const float4 gg = *(const float4*)(g2 + j4 * 4);
;       const float4 yy = make_float4(__uint_as_float(yw[2 * j4] << 16), __uint_as_float(yw[2 * j4] & 0xffff0000u),
;                                     __uint_as_float(yw[2 * j4 + 1] << 16), __uint_as_float(yw[2 * j4 + 1] & 0xffff0000u));
;       float* o = xv + j4 * 4;
;       o[0] = ALPHA * xo.x + gg.x * yy.x; o[1] = ALPHA * xo.y + gg.y * yy.y;
;       o[2] = ALPHA * xo.z + gg.z * yy.z; o[3] = ALPHA * xo.w + gg.w * yy.w;
;       sum += o[0] + o[1] + o[2] + o[3];
;     }
;     float mu = wave_sum(sum) * (1.f / D);
.LBB0_1210:
	v_ashrrev_i32_e32 v33, 31, v32
	v_lshlrev_b64 v[52:53], 12, v[32:33]
	v_lshl_add_u64 v[0:1], v[38:39], 0, v[52:53]
	global_load_dwordx4 v[20:23], v[0:1], off
	global_load_dwordx4 v[16:19], v[0:1], off offset:16
	global_load_dwordx4 v[12:15], v[0:1], off offset:32
	global_load_dwordx4 v[8:11], v[0:1], off offset:48
	v_min_i32_e32 v59, 0x8000, v32
	v_readlane_b32 s0, v250, 1
	v_ashrrev_i32_e32 v59, 13, v59
	s_mul_i32 s0, s0, 5
	v_add_u32_e32 v59, s0, v59
	v_lshlrev_b64 v[0:1], 11, v[32:33]
	v_lshlrev_b32_e32 v196, 2, v34
	v_lshl_add_u64 v[4:5], v[36:37], 0, v[0:1]
	global_load_dwordx4 v[0:3], v[4:5], off
	v_readlane_b32 s4, v250, 19
	v_readlane_b32 s5, v250, 20
	v_lshl_add_u64 v[52:53], v[48:49], 0, v[52:53]
	s_waitcnt vmcnt(4)
	v_mov_b32_e32 v6, v20
	s_waitcnt vmcnt(3)
	v_mov_b32_e32 v7, v16
	v_mov_b32_e32 v24, v21
	v_mov_b32_e32 v25, v17
	v_mov_b32_e32 v26, v22
	v_mov_b32_e32 v27, v18
	v_pk_add_f32 v[6:7], v[6:7], v[24:25]
	v_mov_b32_e32 v28, v23
	v_mov_b32_e32 v29, v19
	s_waitcnt vmcnt(2)
	v_mov_b32_e32 v30, v12
	s_waitcnt vmcnt(1)
	v_mov_b32_e32 v31, v8
	v_mov_b32_e32 v60, v13
	v_mov_b32_e32 v61, v9
	v_pk_add_f32 v[6:7], v[6:7], v[26:27]
	v_mov_b32_e32 v62, v14
	v_mov_b32_e32 v63, v10
	v_pk_add_f32 v[24:25], v[30:31], v[60:61]
	v_pk_add_f32 v[6:7], v[6:7], v[28:29]
	v_mov_b32_e32 v64, v15
	v_mov_b32_e32 v65, v11
	v_pk_add_f32 v[24:25], v[24:25], v[62:63]
	v_add_f32_e32 v6, 0, v6
	v_pk_add_f32 v[24:25], v[24:25], v[64:65]
	v_add_f32_e32 v6, v6, v7
	v_add_f32_e32 v6, v6, v24
	v_add_f32_e32 v24, v6, v25
	ds_bpermute_b32 v25, v35, v24
	v_mov_b64_e32 v[60:61], s[6:7]
	v_mad_i64_i32 v[60:61], s[0:1], v59, s20, v[60:61]
	v_lshl_add_u64 v[80:81], v[60:61], 0, v[196:197]
	s_waitcnt lgkmcnt(0)
	v_add_f32_e32 v62, v24, v25
	ds_bpermute_b32 v63, v54, v62
	s_mov_b64 s[0:1], 0x5000
	global_load_dwordx4 v[4:7], v[4:5], off offset:16
	v_lshl_add_u64 v[76:77], v[80:81], 0, s[0:1]
	global_load_dwordx4 v[28:31], v[42:43], off offset:48
	global_load_dwordx4 v[24:27], v[42:43], off offset:32
	s_waitcnt lgkmcnt(0)
	v_add_f32_e32 v64, v62, v63
	ds_bpermute_b32 v65, v55, v64
	global_load_dwordx4 v[60:63], v[76:77], off offset:48
	s_movk_i32 s0, 0x5000
	v_add_co_u32_e32 v80, vcc, s0, v80
	s_waitcnt lgkmcnt(0)
	v_add_f32_e32 v82, v64, v65
	ds_bpermute_b32 v83, v56, v82
	global_load_dwordx4 v[64:67], v[42:43], off offset:16
	global_load_dwordx4 v[68:71], v[42:43], off
	global_load_dwordx4 v[72:75], v[76:77], off offset:32
	s_nop 0
	global_load_dwordx4 v[76:79], v[76:77], off offset:16
	v_addc_co_u32_e32 v81, vcc, 0, v81, vcc
	s_waitcnt lgkmcnt(0)
	v_add_f32_e32 v84, v82, v83
	ds_bpermute_b32 v85, v57, v84
	global_load_dwordx4 v[80:83], v[80:81], off
	s_waitcnt lgkmcnt(0)
	v_add_f32_e32 v100, v84, v85
	global_load_dwordx4 v[84:87], v[44:45], off offset:48
	global_load_dwordx4 v[88:91], v[44:45], off offset:32
	global_load_dwordx4 v[92:95], v[44:45], off offset:16
	global_load_dwordx4 v[96:99], v[44:45], off
	ds_bpermute_b32 v101, v58, v100
	s_waitcnt lgkmcnt(0)
	v_add_f32_e32 v100, v100, v101
	v_mul_f32_e32 v100, 0x3a800000, v100
	v_pk_add_f32 v[20:21], v[20:21], v[100:101] op_sel_hi:[1,0] neg_lo:[0,1] neg_hi:[0,1]
	v_pk_add_f32 v[22:23], v[22:23], v[100:101] op_sel_hi:[1,0] neg_lo:[0,1] neg_hi:[0,1]
	v_pk_add_f32 v[16:17], v[16:17], v[100:101] op_sel_hi:[1,0] neg_lo:[0,1] neg_hi:[0,1]
	v_pk_add_f32 v[18:19], v[18:19], v[100:101] op_sel_hi:[1,0] neg_lo:[0,1] neg_hi:[0,1]
	v_pk_add_f32 v[12:13], v[12:13], v[100:101] op_sel_hi:[1,0] neg_lo:[0,1] neg_hi:[0,1]
	v_pk_add_f32 v[14:15], v[14:15], v[100:101] op_sel_hi:[1,0] neg_lo:[0,1] neg_hi:[0,1]
	v_pk_add_f32 v[8:9], v[8:9], v[100:101] op_sel_hi:[1,0] neg_lo:[0,1] neg_hi:[0,1]
	v_pk_add_f32 v[10:11], v[10:11], v[100:101] op_sel_hi:[1,0] neg_lo:[0,1] neg_hi:[0,1]
	v_pk_mul_f32 v[100:101], v[20:21], v[20:21]
	v_pk_mul_f32 v[102:103], v[22:23], v[22:23]
	v_add_f32_e32 v100, v100, v101
	v_add_f32_e32 v100, v102, v100
	v_pk_mul_f32 v[104:105], v[16:17], v[16:17]
	v_add_f32_e32 v100, v103, v100
	v_add_f32_e32 v100, v104, v100
	v_pk_mul_f32 v[106:107], v[18:19], v[18:19]
	v_add_f32_e32 v100, v105, v100
	v_add_f32_e32 v100, v106, v100
	v_pk_mul_f32 v[108:109], v[12:13], v[12:13]
	v_add_f32_e32 v100, v107, v100
	v_add_f32_e32 v100, v108, v100
	v_pk_mul_f32 v[110:111], v[14:15], v[14:15]
	v_add_f32_e32 v100, v109, v100
	v_add_f32_e32 v100, v110, v100
	v_pk_mul_f32 v[112:113], v[8:9], v[8:9]
	v_add_f32_e32 v100, v111, v100
	v_add_f32_e32 v100, v112, v100
	v_pk_mul_f32 v[114:115], v[10:11], v[10:11]
	v_add_f32_e32 v100, v113, v100
	v_add_f32_e32 v100, v114, v100
	v_add_f32_e32 v101, v115, v100
	ds_bpermute_b32 v102, v35, v101
	s_waitcnt vmcnt(13)
	v_lshlrev_b32_e32 v100, 16, v0
	s_waitcnt lgkmcnt(0)
	v_add_f32_e32 v103, v101, v102
	ds_bpermute_b32 v104, v54, v103
	v_lshlrev_b32_e32 v102, 16, v2
	v_and_b32_e32 v101, 0xffff0000, v0
	v_lshlrev_b32_e32 v0, 16, v1
	v_and_b32_e32 v1, 0xffff0000, v1
	s_waitcnt lgkmcnt(0)
	v_add_f32_e32 v105, v103, v104
	ds_bpermute_b32 v106, v55, v105
	v_and_b32_e32 v103, 0xffff0000, v2
	v_lshlrev_b32_e32 v2, 16, v3
	v_and_b32_e32 v3, 0xffff0000, v3
	s_waitcnt lgkmcnt(0)
	v_add_f32_e32 v107, v105, v106
	ds_bpermute_b32 v108, v56, v107
	s_waitcnt vmcnt(12)
	v_lshlrev_b32_e32 v104, 16, v4
	v_and_b32_e32 v105, 0xffff0000, v4
	v_lshlrev_b32_e32 v106, 16, v6
	v_lshlrev_b32_e32 v4, 16, v5
	s_waitcnt lgkmcnt(0)
	v_add_f32_e32 v108, v107, v108
	ds_bpermute_b32 v109, v57, v108
	v_and_b32_e32 v107, 0xffff0000, v6
	v_lshlrev_b32_e32 v6, 16, v7
	v_and_b32_e32 v7, 0xffff0000, v7
	s_waitcnt vmcnt(9)
	v_pk_mul_f32 v[6:7], v[62:63], v[6:7]
	s_waitcnt lgkmcnt(0)
; DI void expert_epilogue(const Params& p, int layer, int nrows) {
;     ...
;       const float r0 = rsqrtf(wave_sum(q0) * (1.f / D) + EPS);
;       const float* gm0 = p.ln_gamma + (size_t)(layer * 2 + 0) * D + col;
;       const float* bt0 = p.ln_beta + (size_t)(layer * 2 + 0) * D + col;
; #pragma unroll
;       for (int j4 = 0; j4 < 4; j4++) {
;         const float4 ga = *(const float4*)(gm0 + j4 * 4), be = *(const float4*)(bt0 + j4 * 4);
;         xin[j4 * 4] = xin[j4 * 4] * r0 * ga.x + be.x; xin[j4 * 4 + 1] = xin[j4 * 4 + 1] * r0 * ga.y + be.y;
;         xin[j4 * 4 + 2] = xin[j4 * 4 + 2] * r0 * ga.z + be.z; xin[j4 * 4 + 3] = xin[j4 * 4 + 3] * r0 * ga.w + be.w;
;       }
;     }
;     float xv[16];
;     float sum = 0.f;
;     const uint4 yq0 = *(const uint4*)(Y + (size_t)tk * D + col), yq1 = *(const uint4*)(Y + (size_t)tk * D + col + 8);
;     const u32 yw[8] = {yq0.x, yq0.y, yq0.z, yq0.w, yq1.x, yq1.y, yq1.z, yq1.w};
; #pragma unroll
;     for (int j4 = 0; j4 < 4; j4++) {
;       const float4 xo = make_float4(xin[j4 * 4], xin[j4 * 4 + 1], xin[j4 * 4 + 2], xin[j4 * 4 + 3]);
;       const float4 gg = *(const float4*)(g2 + j4 * 4);
;       const float4 yy = make_float4(__uint_as_float(yw[2 * j4] << 16), __uint_as_float(yw[2 * j4] & 0xffff0000u),
;                                     __uint_as_float(yw[2 * j4 + 1] << 16), __uint_as_float(yw[2 * j4 + 1] & 0xffff0000u));
;       float* o = xv + j4 * 4;
;       o[0] = ALPHA * xo.x + gg.x * yy.x; o[1] = ALPHA * xo.y + gg.y * yy.y;
;       o[2] = ALPHA * xo.z + gg.z * yy.z; o[3] = ALPHA * xo.w + gg.w * yy.w;
;       sum += o[0] + o[1] + o[2] + o[3];
;     }
;     float mu = wave_sum(sum) * (1.f / D);
;     float q = 0.f;
; #pragma unroll
;     for (int j = 0; j < 16; j++) { xv[j] -= mu; q += xv[j] * xv[j]; }
;     float rstd = rsqrtf(wave_sum(q) * (1.f / D) + EPS);
;     float* dstx = (last ? p.out : p.X) + (size_t)tk * D + col;
;     float s2 = 0.f;
;     float4 gmq[4], btq[4];
; #pragma unroll
;     for (int j4 = 0; j4 < 4; j4++) { gmq[j4] = *(const float4*)(gm + j4 * 4); btq[j4] = *(const float4*)(bt + j4 * 4); }
; #pragma unroll
;     for (int j4 = 0; j4 < 4; j4++) {
;       const float4 gmv = gmq[j4];
;       const float4 btv = btq[j4];
;       float* o = xv + j4 * 4;
;       o[0] = o[0] * rstd * gmv.x + btv.x; o[1] = o[1] * rstd * gmv.y + btv.y;
	v_add_f32_e32 v108, v108, v109
	ds_bpermute_b32 v109, v58, v108
	s_waitcnt vmcnt(6)
	v_pk_mul_f32 v[62:63], v[72:73], v[104:105]
	s_waitcnt vmcnt(5)
	v_pk_mul_f32 v[2:3], v[78:79], v[2:3]
	v_and_b32_e32 v5, 0xffff0000, v5
	v_pk_mul_f32 v[60:61], v[60:61], v[106:107]
	s_waitcnt lgkmcnt(0)
	v_add_f32_e32 v72, v108, v109
	v_fmamk_f32 v72, v72, 0x3a800000, v224
	v_mul_f32_e32 v73, 0x4b800000, v72
	v_cmp_gt_f32_e32 vcc, s34, v72
	v_pk_mul_f32 v[4:5], v[74:75], v[4:5]
	s_waitcnt vmcnt(4)
	v_pk_mul_f32 v[74:75], v[80:81], v[100:101]
	v_cndmask_b32_e32 v72, v72, v73, vcc
	v_rsq_f32_e32 v78, v72
	v_pk_mul_f32 v[72:73], v[76:77], v[102:103]
	v_pk_mul_f32 v[0:1], v[82:83], v[0:1]
	v_mul_f32_e32 v76, 0x45800000, v78
	v_cndmask_b32_e32 v76, v78, v76, vcc
	v_pk_mul_f32 v[20:21], v[20:21], v[76:77] op_sel_hi:[1,0]
	v_pk_mul_f32 v[16:17], v[16:17], v[76:77] op_sel_hi:[1,0]
	v_pk_mul_f32 v[12:13], v[12:13], v[76:77] op_sel_hi:[1,0]
	v_pk_mul_f32 v[8:9], v[8:9], v[76:77] op_sel_hi:[1,0]
	v_pk_mul_f32 v[22:23], v[22:23], v[76:77] op_sel_hi:[1,0]
	v_pk_mul_f32 v[18:19], v[18:19], v[76:77] op_sel_hi:[1,0]
	v_pk_mul_f32 v[10:11], v[10:11], v[76:77] op_sel_hi:[1,0]
	s_waitcnt vmcnt(3)
	v_pk_fma_f32 v[8:9], v[28:29], v[8:9], v[84:85]
	s_waitcnt vmcnt(2)
	v_pk_fma_f32 v[12:13], v[24:25], v[12:13], v[88:89]
	s_waitcnt vmcnt(1)
	v_pk_fma_f32 v[16:17], v[64:65], v[16:17], v[92:93]
	s_waitcnt vmcnt(0)
	v_pk_fma_f32 v[20:21], v[68:69], v[20:21], v[96:97]
	v_pk_fma_f32 v[10:11], v[30:31], v[10:11], v[86:87]
	v_pk_fma_f32 v[18:19], v[66:67], v[18:19], v[94:95]
	v_pk_fma_f32 v[22:23], v[70:71], v[22:23], v[98:99]
	v_pk_fma_f32 v[60:61], v[8:9], s[90:91], v[60:61] op_sel_hi:[1,0,1]
	v_pk_fma_f32 v[62:63], v[12:13], s[90:91], v[62:63] op_sel_hi:[1,0,1]
	v_pk_fma_f32 v[70:71], v[16:17], s[90:91], v[72:73] op_sel_hi:[1,0,1]
	v_pk_fma_f32 v[74:75], v[20:21], s[90:91], v[74:75] op_sel_hi:[1,0,1]
	v_pk_mul_f32 v[14:15], v[14:15], v[76:77] op_sel_hi:[1,0]
	v_pk_fma_f32 v[64:65], v[10:11], s[90:91], v[6:7] op_sel_hi:[1,0,1]
	v_pk_fma_f32 v[68:69], v[18:19], s[90:91], v[2:3] op_sel_hi:[1,0,1]
	v_pk_fma_f32 v[72:73], v[22:23], s[90:91], v[0:1] op_sel_hi:[1,0,1]
	v_mov_b32_e32 v0, v62
	v_mov_b32_e32 v1, v60
	v_mov_b32_e32 v2, v63
	v_mov_b32_e32 v3, v61
	v_mov_b32_e32 v8, v74
	v_mov_b32_e32 v9, v70
	v_mov_b32_e32 v10, v75
	v_mov_b32_e32 v11, v71
	v_pk_fma_f32 v[14:15], v[26:27], v[14:15], v[90:91]
	v_mov_b32_e32 v12, v72
	v_mov_b32_e32 v13, v68
	v_pk_add_f32 v[0:1], v[0:1], v[2:3]
	v_pk_add_f32 v[2:3], v[8:9], v[10:11]
	v_pk_fma_f32 v[66:67], v[14:15], s[90:91], v[4:5] op_sel_hi:[1,0,1]
	v_mov_b32_e32 v14, v73
	v_mov_b32_e32 v15, v69
	v_pk_add_f32 v[2:3], v[12:13], v[2:3]
	v_mov_b32_e32 v4, v66
	v_mov_b32_e32 v5, v64
	v_pk_add_f32 v[2:3], v[14:15], v[2:3]
	v_mov_b32_e32 v6, v67
	v_mov_b32_e32 v7, v65
	v_pk_add_f32 v[0:1], v[4:5], v[0:1]
	v_add_f32_e32 v2, 0, v2
	v_pk_add_f32 v[0:1], v[6:7], v[0:1]
	v_add_f32_e32 v2, v2, v3
	v_add_f32_e32 v0, v2, v0
	v_add_f32_e32 v0, v0, v1
	ds_bpermute_b32 v1, v35, v0
	s_andn2_b64 vcc, exec, s[4:5]
	s_waitcnt lgkmcnt(0)
	v_add_f32_e32 v0, v0, v1
	ds_bpermute_b32 v1, v54, v0
	s_waitcnt lgkmcnt(0)
	v_add_f32_e32 v0, v0, v1
	ds_bpermute_b32 v1, v55, v0
	s_waitcnt lgkmcnt(0)
	v_add_f32_e32 v0, v0, v1
	ds_bpermute_b32 v1, v56, v0
	s_waitcnt lgkmcnt(0)
	v_add_f32_e32 v16, v0, v1
	ds_bpermute_b32 v17, v57, v16
	s_waitcnt lgkmcnt(0)
	v_add_f32_e32 v76, v16, v17
	ds_bpermute_b32 v77, v58, v76
	s_waitcnt lgkmcnt(0)
	v_add_f32_e32 v76, v76, v77
	v_mul_f32_e32 v76, 0x3a800000, v76
	v_pk_add_f32 v[74:75], v[74:75], v[76:77] op_sel_hi:[1,0] neg_lo:[0,1] neg_hi:[0,1]
	v_pk_add_f32 v[72:73], v[72:73], v[76:77] op_sel_hi:[1,0] neg_lo:[0,1] neg_hi:[0,1]
	v_pk_add_f32 v[70:71], v[70:71], v[76:77] op_sel_hi:[1,0] neg_lo:[0,1] neg_hi:[0,1]
	v_pk_add_f32 v[68:69], v[68:69], v[76:77] op_sel_hi:[1,0] neg_lo:[0,1] neg_hi:[0,1]
	v_pk_add_f32 v[62:63], v[62:63], v[76:77] op_sel_hi:[1,0] neg_lo:[0,1] neg_hi:[0,1]
	v_pk_add_f32 v[66:67], v[66:67], v[76:77] op_sel_hi:[1,0] neg_lo:[0,1] neg_hi:[0,1]
	v_pk_add_f32 v[60:61], v[60:61], v[76:77] op_sel_hi:[1,0] neg_lo:[0,1] neg_hi:[0,1]
	v_pk_add_f32 v[64:65], v[64:65], v[76:77] op_sel_hi:[1,0] neg_lo:[0,1] neg_hi:[0,1]
	v_pk_mul_f32 v[76:77], v[74:75], v[74:75]
	v_pk_mul_f32 v[78:79], v[72:73], v[72:73]
	v_add_f32_e32 v76, v76, v77
	v_add_f32_e32 v76, v78, v76
	v_pk_mul_f32 v[80:81], v[70:71], v[70:71]
	v_add_f32_e32 v76, v79, v76
	v_add_f32_e32 v76, v80, v76
	v_pk_mul_f32 v[82:83], v[68:69], v[68:69]
	v_add_f32_e32 v76, v81, v76
	v_add_f32_e32 v76, v82, v76
	v_pk_mul_f32 v[84:85], v[62:63], v[62:63]
	v_add_f32_e32 v76, v83, v76
	v_add_f32_e32 v76, v84, v76
	v_pk_mul_f32 v[86:87], v[66:67], v[66:67]
	v_add_f32_e32 v76, v85, v76
	v_add_f32_e32 v76, v86, v76
	v_pk_mul_f32 v[88:89], v[60:61], v[60:61]
	v_add_f32_e32 v76, v87, v76
	v_add_f32_e32 v76, v88, v76
	v_pk_mul_f32 v[90:91], v[64:65], v[64:65]
	v_add_f32_e32 v76, v89, v76
	v_add_f32_e32 v76, v90, v76
	v_add_f32_e32 v76, v91, v76
	ds_bpermute_b32 v77, v35, v76
	s_waitcnt lgkmcnt(0)
	v_add_f32_e32 v76, v76, v77
	ds_bpermute_b32 v77, v54, v76
	s_waitcnt lgkmcnt(0)
	v_add_f32_e32 v76, v76, v77
	ds_bpermute_b32 v77, v55, v76
	s_waitcnt lgkmcnt(0)
	v_add_f32_e32 v76, v76, v77
	ds_bpermute_b32 v77, v56, v76
	s_waitcnt lgkmcnt(0)
	v_add_f32_e32 v76, v76, v77
	ds_bpermute_b32 v77, v57, v76
	s_waitcnt lgkmcnt(0)
	v_add_f32_e32 v76, v76, v77
	ds_bpermute_b32 v77, v58, v76
	s_waitcnt lgkmcnt(0)
	v_add_f32_e32 v76, v76, v77
	v_fmamk_f32 v76, v76, 0x3a800000, v224
	v_mul_f32_e32 v77, 0x4b800000, v76
	v_cmp_gt_f32_e64 s[0:1], s34, v76
	s_nop 1
	v_cndmask_b32_e64 v76, v76, v77, s[0:1]
	v_rsq_f32_e32 v76, v76
	s_nop 0
	v_mul_f32_e32 v77, 0x45800000, v76
	v_cndmask_b32_e64 v76, v76, v77, s[0:1]
	v_pk_mul_f32 v[74:75], v[74:75], v[76:77] op_sel_hi:[1,0]
	v_pk_mul_f32 v[72:73], v[72:73], v[76:77] op_sel_hi:[1,0]
	v_pk_mul_f32 v[70:71], v[70:71], v[76:77] op_sel_hi:[1,0]
	v_pk_mul_f32 v[68:69], v[68:69], v[76:77] op_sel_hi:[1,0]
	v_pk_mul_f32 v[62:63], v[62:63], v[76:77] op_sel_hi:[1,0]
	v_pk_mul_f32 v[66:67], v[66:67], v[76:77] op_sel_hi:[1,0]
	v_pk_mul_f32 v[60:61], v[60:61], v[76:77] op_sel_hi:[1,0]
	v_pk_mul_f32 v[64:65], v[64:65], v[76:77] op_sel_hi:[1,0]
	s_waitcnt vmcnt(0)
	v_pk_fma_f32 v[0:1], v[116:117], v[74:75], v[144:145]
	v_pk_fma_f32 v[2:3], v[118:119], v[72:73], v[146:147]
	v_pk_fma_f32 v[4:5], v[120:121], v[70:71], v[140:141]
	v_pk_fma_f32 v[6:7], v[122:123], v[68:69], v[142:143]
	v_pk_fma_f32 v[8:9], v[124:125], v[62:63], v[136:137]
	v_pk_fma_f32 v[10:11], v[126:127], v[66:67], v[138:139]
	v_pk_fma_f32 v[12:13], v[128:129], v[60:61], v[132:133]
	v_pk_fma_f32 v[14:15], v[130:131], v[64:65], v[134:135]
	global_store_dwordx4 v[52:53], v[0:3], off
	global_store_dwordx4 v[52:53], v[4:7], off offset:16
	global_store_dwordx4 v[52:53], v[8:11], off offset:32
	global_store_dwordx4 v[52:53], v[12:15], off offset:48
	s_cbranch_vccnz .LBB0_1209
; DI u32 pack2(float a, float b) { f32x2v v = {a, b}; return __builtin_bit_cast(u32, __builtin_convertvector(v, bf16x2v)); }
; DI void expert_epilogue(const Params& p, int layer, int nrows) {
;     ...
;     if (!last) {
;       float mu2 = wave_sum(s2) * (1.f / D);
;       float q2 = 0.f;
; #pragma unroll
;       for (int j = 0; j < 16; j++) { xv[j] -= mu2; q2 += xv[j] * xv[j]; }
;       float rstd2 = rsqrtf(wave_sum(q2) * (1.f / D) + EPS);
;       const float* sh = ada_ptr(p, layer + 1, b, 0) + col;
;       const float* sc = ada_ptr(p, layer + 1, b, 1) + col;
;       u32 ow[8];
; #pragma unroll
;       for (int j = 0; j < 8; j++) {
;         float y0 = xv[2 * j] * rstd2 * (1.f + sc[2 * j]) + sh[2 * j];
;         float y1 = xv[2 * j + 1] * rstd2 * (1.f + sc[2 * j + 1]) + sh[2 * j + 1];
;         ow[j] = pack2(y0, y1);
;       }
;       *(uint4*)(p.H + (size_t)tk * D + col) = make_uint4(ow[0], ow[1], ow[2], ow[3]);
;       *(uint4*)(p.H + (size_t)tk * D + col + 8) = make_uint4(ow[4], ow[5], ow[6], ow[7]);
	v_mov_b32_e32 v16, v4
	v_mov_b32_e32 v17, v0
	v_mov_b32_e32 v18, v5
	v_mov_b32_e32 v19, v1
	v_pk_add_f32 v[16:17], v[16:17], v[18:19]
	v_mov_b32_e32 v18, v6
	v_mov_b32_e32 v19, v2
	v_pk_add_f32 v[16:17], v[18:19], v[16:17]
	v_mov_b32_e32 v18, v7
	v_mov_b32_e32 v19, v3
	v_pk_add_f32 v[16:17], v[18:19], v[16:17]
	v_mov_b32_e32 v18, v13
	v_add_f32_e32 v17, 0, v17
	v_add_f32_e32 v20, v16, v17
	v_mov_b32_e32 v16, v12
	v_mov_b32_e32 v17, v8
	v_mov_b32_e32 v19, v9
	v_pk_add_f32 v[16:17], v[16:17], v[18:19]
	v_mov_b32_e32 v18, v14
	v_mov_b32_e32 v19, v10
	v_pk_add_f32 v[16:17], v[18:19], v[16:17]
	v_mov_b32_e32 v18, v15
	v_mov_b32_e32 v19, v11
	v_pk_add_f32 v[16:17], v[18:19], v[16:17]
	v_add_u32_e32 v18, 5, v59
	v_add_f32_e32 v17, v17, v20
	v_add_f32_e32 v16, v16, v17
	ds_bpermute_b32 v17, v35, v16
	s_waitcnt lgkmcnt(0)
	v_add_f32_e32 v16, v16, v17
	ds_bpermute_b32 v17, v54, v16
	s_waitcnt lgkmcnt(0)
	v_add_f32_e32 v16, v16, v17
	ds_bpermute_b32 v17, v55, v16
	s_waitcnt lgkmcnt(0)
	v_add_f32_e32 v16, v16, v17
	ds_bpermute_b32 v17, v56, v16
	s_waitcnt lgkmcnt(0)
	v_add_f32_e32 v28, v16, v17
	ds_bpermute_b32 v29, v57, v28
	v_mov_b64_e32 v[16:17], s[6:7]
	v_mad_i64_i32 v[16:17], s[0:1], v18, s20, v[16:17]
	v_lshl_add_u64 v[52:53], v[16:17], 0, v[196:197]
	s_waitcnt lgkmcnt(0)
	v_add_f32_e32 v59, v28, v29
	ds_bpermute_b32 v60, v58, v59
	s_mov_b64 s[0:1], 0x1000
	v_add_co_u32_e32 v28, vcc, s35, v52
	v_lshl_add_u64 v[24:25], v[52:53], 0, s[0:1]
	s_nop 0
	v_addc_co_u32_e32 v29, vcc, 0, v53, vcc
	global_load_dwordx4 v[16:19], v[24:25], off offset:48
	global_load_dwordx4 v[20:23], v[24:25], off offset:32
	s_nop 0
	global_load_dwordx4 v[24:27], v[24:25], off offset:16
	s_waitcnt lgkmcnt(0)
	v_add_f32_e32 v59, v59, v60
	global_load_dwordx4 v[28:31], v[28:29], off
	s_nop 0
	global_load_dwordx4 v[60:63], v[52:53], off offset:16
	global_load_dwordx4 v[64:67], v[52:53], off
	v_mul_f32_e32 v72, 0x3a800000, v59
	v_pk_add_f32 v[74:75], v[14:15], v[72:73] op_sel_hi:[1,0] neg_lo:[0,1] neg_hi:[0,1]
	v_pk_add_f32 v[78:79], v[12:13], v[72:73] op_sel_hi:[1,0] neg_lo:[0,1] neg_hi:[0,1]
	global_load_dwordx4 v[12:15], v[52:53], off offset:48
	global_load_dwordx4 v[68:71], v[52:53], off offset:32
	v_pk_add_f32 v[0:1], v[0:1], v[72:73] op_sel_hi:[1,0] neg_lo:[0,1] neg_hi:[0,1]
	v_pk_add_f32 v[10:11], v[10:11], v[72:73] op_sel_hi:[1,0] neg_lo:[0,1] neg_hi:[0,1]
	v_pk_add_f32 v[8:9], v[8:9], v[72:73] op_sel_hi:[1,0] neg_lo:[0,1] neg_hi:[0,1]
	v_pk_add_f32 v[6:7], v[6:7], v[72:73] op_sel_hi:[1,0] neg_lo:[0,1] neg_hi:[0,1]
	v_pk_add_f32 v[4:5], v[4:5], v[72:73] op_sel_hi:[1,0] neg_lo:[0,1] neg_hi:[0,1]
	v_pk_add_f32 v[2:3], v[2:3], v[72:73] op_sel_hi:[1,0] neg_lo:[0,1] neg_hi:[0,1]
	v_pk_mul_f32 v[72:73], v[0:1], v[0:1]
	v_pk_mul_f32 v[88:89], v[2:3], v[2:3]
	v_add_f32_e32 v59, v72, v73
	v_add_f32_e32 v59, v88, v59
	v_pk_mul_f32 v[86:87], v[4:5], v[4:5]
	v_add_f32_e32 v59, v89, v59
	v_add_f32_e32 v59, v86, v59
	v_pk_mul_f32 v[84:85], v[6:7], v[6:7]
	v_add_f32_e32 v59, v87, v59
	v_add_f32_e32 v59, v84, v59
	v_pk_mul_f32 v[82:83], v[8:9], v[8:9]
	v_add_f32_e32 v59, v85, v59
	v_add_f32_e32 v59, v82, v59
	v_pk_mul_f32 v[52:53], v[10:11], v[10:11]
	v_add_f32_e32 v59, v83, v59
	v_add_f32_e32 v52, v52, v59
	v_pk_mul_f32 v[80:81], v[78:79], v[78:79]
	v_add_f32_e32 v52, v53, v52
	v_add_f32_e32 v52, v80, v52
	v_pk_mul_f32 v[76:77], v[74:75], v[74:75]
	v_add_f32_e32 v52, v81, v52
	v_add_f32_e32 v52, v76, v52
	v_add_f32_e32 v52, v77, v52
	ds_bpermute_b32 v53, v35, v52
	s_waitcnt lgkmcnt(0)
	v_add_f32_e32 v52, v52, v53
	ds_bpermute_b32 v53, v54, v52
	s_waitcnt lgkmcnt(0)
	v_add_f32_e32 v52, v52, v53
	ds_bpermute_b32 v53, v55, v52
	s_waitcnt lgkmcnt(0)
	v_add_f32_e32 v52, v52, v53
	ds_bpermute_b32 v53, v56, v52
	s_waitcnt lgkmcnt(0)
	v_add_f32_e32 v59, v52, v53
	ds_bpermute_b32 v72, v57, v59
	v_lshlrev_b64 v[52:53], 10, v[32:33]
	s_waitcnt lgkmcnt(0)
	v_add_f32_e32 v33, v59, v72
	ds_bpermute_b32 v59, v58, v33
	s_waitcnt lgkmcnt(0)
	v_add_f32_e32 v33, v33, v59
	v_fmamk_f32 v33, v33, 0x3a800000, v224
	v_mul_f32_e32 v59, 0x4b800000, v33
	v_cmp_gt_f32_e32 vcc, s34, v33
	s_waitcnt vmcnt(7)
	v_pk_add_f32 v[16:17], v[16:17], 1.0 op_sel_hi:[1,0]
	v_cndmask_b32_e32 v33, v33, v59, vcc
	v_rsq_f32_e32 v33, v33
	s_waitcnt vmcnt(5)
	v_pk_add_f32 v[26:27], v[26:27], 1.0 op_sel_hi:[1,0]
	s_waitcnt vmcnt(4)
	v_pk_add_f32 v[30:31], v[30:31], 1.0 op_sel_hi:[1,0]
	v_pk_add_f32 v[28:29], v[28:29], 1.0 op_sel_hi:[1,0]
	v_mul_f32_e32 v59, 0x45800000, v33
	v_cndmask_b32_e32 v72, v33, v59, vcc
	v_pk_mul_f32 v[0:1], v[0:1], v[72:73] op_sel_hi:[1,0]
	v_pk_mul_f32 v[2:3], v[2:3], v[72:73] op_sel_hi:[1,0]
	s_waitcnt vmcnt(2)
	v_pk_fma_f32 v[0:1], v[28:29], v[0:1], v[64:65]
	v_pk_fma_f32 v[2:3], v[30:31], v[2:3], v[66:67]
	v_pk_add_f32 v[24:25], v[24:25], 1.0 op_sel_hi:[1,0]
	v_cvt_pk_bf16_f32 v0, v0, v1
	v_cvt_pk_bf16_f32 v1, v2, v3
	v_pk_mul_f32 v[2:3], v[4:5], v[72:73] op_sel_hi:[1,0]
	v_pk_mul_f32 v[4:5], v[6:7], v[72:73] op_sel_hi:[1,0]
	v_pk_fma_f32 v[2:3], v[24:25], v[2:3], v[60:61]
	v_pk_fma_f32 v[4:5], v[26:27], v[4:5], v[62:63]
	v_pk_add_f32 v[22:23], v[22:23], 1.0 op_sel_hi:[1,0]
	v_pk_add_f32 v[20:21], v[20:21], 1.0 op_sel_hi:[1,0]
	v_cvt_pk_bf16_f32 v2, v2, v3
	v_cvt_pk_bf16_f32 v3, v4, v5
	v_pk_mul_f32 v[4:5], v[8:9], v[72:73] op_sel_hi:[1,0]
	v_pk_mul_f32 v[6:7], v[10:11], v[72:73] op_sel_hi:[1,0]
	s_waitcnt vmcnt(0)
	v_pk_fma_f32 v[4:5], v[20:21], v[4:5], v[68:69]
	v_pk_fma_f32 v[6:7], v[22:23], v[6:7], v[70:71]
	v_cvt_pk_bf16_f32 v4, v4, v5
	v_cvt_pk_bf16_f32 v5, v6, v7
	v_pk_mul_f32 v[6:7], v[78:79], v[72:73] op_sel_hi:[1,0]
	v_pk_mul_f32 v[8:9], v[74:75], v[72:73] op_sel_hi:[1,0]
	v_pk_add_f32 v[10:11], v[18:19], 1.0 op_sel_hi:[1,0]
	v_pk_fma_f32 v[6:7], v[16:17], v[6:7], v[12:13]
	v_pk_fma_f32 v[8:9], v[8:9], v[10:11], v[14:15]
	v_cvt_pk_bf16_f32 v6, v6, v7
	v_cvt_pk_bf16_f32 v7, v8, v9
	v_lshl_add_u64 v[8:9], v[52:53], 1, v[50:51]
	global_store_dwordx4 v[8:9], v[0:3], off
	global_store_dwordx4 v[8:9], v[4:7], off offset:16
	s_branch .LBB0_1209
